# P2/P6/P8 residual epilogues: read-once f32 residual loads and f32 result stores made non-temporal so they do not evict the next tile's GEMM operands
# baseline (speedup 1.0000x reference)
; __device__ __forceinline__ unsigned cvt_pk_bf16(float lo, float hi) { unsigned r; asm volatile("v_cvt_pk_bf16_f32 %0, %1, %2" : "=v"(r) : "v"(lo), "v"(hi)); return r; }
; #define SCHED_BAR() __builtin_amdgcn_sched_barrier(0)
;     __device__ __forceinline__ void operator()(const Acc& acc, const Unit& u, int wr, int wc, int fr, int fq) const {
;     ...
;             for (int m = 0; m < 4; ++m) {
;                 const int row = u.pm * 256 + ai * 128 + wr * 64 + m * 16 + fr; const int rr = row < MREAL ? row : 0;
;                 const float* res = ((MODE == 0) ? xin_row(P, rr) : (const float*)x1_row(P, rr)) + colb;
; #pragma unroll
;                 for (int bj = 0; bj < 2; ++bj)
; #pragma unroll
;                     for (int n = 0; n < 2; ++n) R[m][bj][n] = *(const f32x4*)(res + bj * 32 + n * 4);
;             }
;             SCHED_BAR();
; #pragma unroll
;             for (int m = 0; m < 4; ++m) {
;                 const int row = u.pm * 256 + ai * 128 + wr * 64 + m * 16 + fr;
;                 const bool ok = row < MREAL; const int rr = ok ? row : 0;
;                 float* dst = ((MODE == 2) ? y_row(P, rr) : x1_row(P, rr)) + colb;
;                 float part = 0.f;
; #pragma unroll
;                 for (int bj = 0; bj < 2; ++bj) {
;                     const f32x4 o0 = R[m][bj][0] + acc[ai][bj][m][0] * sc, o1 = R[m][bj][1] + acc[ai][bj][m][1] * sc;
;                     if (ok) {
;                         *(f32x4*)(dst + bj * 32) = o0; *(f32x4*)(dst + bj * 32 + 4) = o1;
;                         if (MODE != 2) { part += ((o0[0] * o0[0] + o0[1] * o0[1]) + (o0[2] * o0[2] + o0[3] * o0[3])) + ((o1[0] * o1[0] + o1[1] * o1[1]) + (o1[2] * o1[2] + o1[3] * o1[3]));
;                             u32x4 w; w.x = cvt_pk_bf16(o0[0], o0[1]); w.y = cvt_pk_bf16(o0[2], o0[3]); w.z = cvt_pk_bf16(o1[0], o1[1]); w.w = cvt_pk_bf16(o1[2], o1[3]);
;                             *(u32x4*)(xb + (size_t)row * DM + colb + bj * 32) = w; }
.LBB0_551:
	v_lshl_add_u32 v216, s12, 8, v235
	v_cmp_gt_i32_e64 s[16:17], s61, v216
	v_readlane_b32 s64, v254, 19
	v_readlane_b32 s65, v254, 20
	v_cndmask_b32_e64 v128, 0, v216, s[16:17]
	v_add_u32_e32 v130, 0xffff8000, v128
	v_ashrrev_i32_e32 v129, 31, v128
	v_cmp_gt_i32_e64 s[0:1], s53, v128
	v_readlane_b32 s66, v254, 21
	v_readlane_b32 s67, v254, 22
	v_lshl_or_b32 v212, s13, 8, v237
	v_cndmask_b32_e64 v129, 0, v129, s[0:1]
	v_cndmask_b32_e64 v128, v130, v128, s[0:1]
	v_mov_b32_e32 v132, s67
	v_mov_b32_e32 v133, s65
	v_mov_b32_e32 v134, s66
	v_mov_b32_e32 v135, s64
	v_ashrrev_i32_e32 v213, 31, v212
	v_cndmask_b32_e64 v131, v132, v133, s[0:1]
	v_cndmask_b32_e64 v130, v134, v135, s[0:1]
	v_lshlrev_b64 v[230:231], 12, v[128:129]
	v_lshl_add_u64 v[128:129], v[130:131], 0, v[230:231]
	v_lshlrev_b64 v[214:215], 2, v[212:213]
	v_or_b32_e32 v224, 16, v216
	v_lshl_add_u64 v[128:129], v[128:129], 0, v[214:215]
	v_cmp_gt_i32_e64 s[12:13], s61, v224
	global_load_dwordx4 v[188:191], v[128:129], off offset:16 nt
	global_load_dwordx4 v[184:187], v[128:129], off nt
	global_load_dwordx4 v[180:183], v[128:129], off offset:144 nt
	global_load_dwordx4 v[176:179], v[128:129], off offset:128 nt
	v_cndmask_b32_e64 v128, 0, v224, s[12:13]
	v_add_u32_e32 v130, 0xffff8000, v128
	v_ashrrev_i32_e32 v129, 31, v128
	v_cmp_gt_i32_e64 s[18:19], s53, v128
	v_or_b32_e32 v220, 32, v216
	v_cmp_gt_i32_e64 s[8:9], s61, v220
	v_cndmask_b32_e64 v129, 0, v129, s[18:19]
	v_cndmask_b32_e64 v128, v130, v128, s[18:19]
	v_cndmask_b32_e64 v131, v132, v133, s[18:19]
	v_cndmask_b32_e64 v130, v134, v135, s[18:19]
	v_lshlrev_b64 v[228:229], 12, v[128:129]
	v_lshl_add_u64 v[128:129], v[130:131], 0, v[228:229]
	v_lshl_add_u64 v[128:129], v[128:129], 0, v[214:215]
	global_load_dwordx4 v[172:175], v[128:129], off offset:16 nt
	global_load_dwordx4 v[168:171], v[128:129], off nt
	global_load_dwordx4 v[164:167], v[128:129], off offset:144 nt
	global_load_dwordx4 v[160:163], v[128:129], off offset:128 nt
	v_cndmask_b32_e64 v128, 0, v220, s[8:9]
	v_add_u32_e32 v130, 0xffff8000, v128
	v_ashrrev_i32_e32 v129, 31, v128
	v_cmp_gt_i32_e64 s[14:15], s53, v128
	v_or_b32_e32 v218, 48, v216
	v_cmp_gt_i32_e32 vcc, s61, v218
	v_cndmask_b32_e64 v129, 0, v129, s[14:15]
	v_cndmask_b32_e64 v128, v130, v128, s[14:15]
	v_cndmask_b32_e64 v131, v132, v133, s[14:15]
	v_cndmask_b32_e64 v130, v134, v135, s[14:15]
	v_lshlrev_b64 v[226:227], 12, v[128:129]
	v_lshl_add_u64 v[128:129], v[130:131], 0, v[226:227]
	v_lshl_add_u64 v[128:129], v[128:129], 0, v[214:215]
	global_load_dwordx4 v[156:159], v[128:129], off offset:16 nt
	global_load_dwordx4 v[152:155], v[128:129], off nt
	global_load_dwordx4 v[148:151], v[128:129], off offset:144 nt
	global_load_dwordx4 v[144:147], v[128:129], off offset:128 nt
	v_cndmask_b32_e32 v128, 0, v218, vcc
	v_add_u32_e32 v130, 0xffff8000, v128
	v_ashrrev_i32_e32 v129, 31, v128
	v_cmp_gt_i32_e64 s[10:11], s53, v128
	v_readlane_b32 s68, v254, 23
	v_readlane_b32 s69, v254, 24
	v_cndmask_b32_e64 v129, 0, v129, s[10:11]
	v_cndmask_b32_e64 v128, v130, v128, s[10:11]
	v_cndmask_b32_e64 v131, v132, v133, s[10:11]
	v_cndmask_b32_e64 v130, v134, v135, s[10:11]
	v_lshlrev_b64 v[222:223], 12, v[128:129]
	v_lshl_add_u64 v[128:129], v[130:131], 0, v[222:223]
	v_lshl_add_u64 v[128:129], v[128:129], 0, v[214:215]
	global_load_dwordx4 v[140:143], v[128:129], off offset:16 nt
	global_load_dwordx4 v[136:139], v[128:129], off nt
	global_load_dwordx4 v[132:135], v[128:129], off offset:144 nt
	s_nop 0
	global_load_dwordx4 v[128:131], v[128:129], off offset:128 nt
	v_readlane_b32 s70, v254, 25
	v_readlane_b32 s71, v254, 26
	v_readlane_b32 s72, v254, 27
	v_readlane_b32 s73, v254, 28
	v_readlane_b32 s74, v254, 29
	v_readlane_b32 s75, v254, 30
	v_readlane_b32 s76, v254, 31
	v_readlane_b32 s77, v254, 32
	v_readlane_b32 s78, v254, 33
	v_readlane_b32 s79, v254, 34
	v_readlane_b32 s64, v254, 1
	v_readlane_b32 s66, v254, 3
	v_readlane_b32 s67, v254, 4
	v_readlane_b32 s70, v254, 7
	v_readlane_b32 s71, v254, 8
	s_mov_b64 s[66:67], s[70:71]
	v_mov_b32_e32 v217, s58
	v_mov_b32_e32 v219, s67
	v_cndmask_b32_e64 v233, v217, v219, s[0:1]
	v_mov_b32_e32 v217, s57
	v_mov_b32_e32 v219, s66
	v_cndmask_b32_e64 v232, v217, v219, s[0:1]
	v_lshl_add_u64 v[230:231], v[232:233], 0, v[230:231]
	v_ashrrev_i32_e32 v217, 31, v216
	v_readlane_b32 s0, v254, 49
	v_lshl_add_u64 v[232:233], v[230:231], 0, v[214:215]
	v_lshlrev_b64 v[230:231], 11, v[216:217]
	v_readlane_b32 s1, v254, 50
	v_mov_b32_e32 v219, 0
	v_readlane_b32 s65, v254, 2
	v_lshl_add_u64 v[230:231], s[0:1], 0, v[230:231]
	v_lshl_add_u64 v[230:231], v[212:213], 1, v[230:231]
	v_readlane_b32 s68, v254, 5
	v_readlane_b32 s69, v254, 6
	s_and_saveexec_b64 s[0:1], s[16:17]
	s_cbranch_execz .LBB0_553
	s_waitcnt vmcnt(0)
	v_pk_fma_f32 v[124:125], v[124:125], 0.5, v[188:189] op_sel_hi:[1,0,1]
	v_pk_fma_f32 v[120:121], v[120:121], 0.5, v[184:185] op_sel_hi:[1,0,1]
	v_pk_fma_f32 v[126:127], v[126:127], 0.5, v[190:191] op_sel_hi:[1,0,1]
	v_pk_fma_f32 v[122:123], v[122:123], 0.5, v[186:187] op_sel_hi:[1,0,1]
	v_mov_b32_e32 v186, v121
	v_mov_b32_e32 v187, v125
	v_mov_b32_e32 v184, v120
	v_mov_b32_e32 v185, v124
	v_pk_mul_f32 v[186:187], v[186:187], v[186:187]
	v_mov_b32_e32 v188, v123
	v_mov_b32_e32 v189, v127
	v_pk_fma_f32 v[184:185], v[184:185], v[184:185], v[186:187]
	v_mov_b32_e32 v186, v122
	v_mov_b32_e32 v187, v126
	v_pk_mul_f32 v[188:189], v[188:189], v[188:189]
	global_store_dwordx4 v[232:233], v[120:123], off nt
	global_store_dwordx4 v[232:233], v[124:127], off offset:16 nt
	v_pk_fma_f32 v[186:187], v[186:187], v[186:187], v[188:189]
	v_cvt_pk_bf16_f32 v120, v120, v121
	v_cvt_pk_bf16_f32 v121, v122, v123
	v_cvt_pk_bf16_f32 v122, v124, v125
	v_cvt_pk_bf16_f32 v123, v126, v127
	global_store_dwordx4 v[230:231], v[120:123], off
	v_pk_add_f32 v[184:185], v[184:185], v[186:187]
	s_nop 0
	v_add_f32_e32 v219, v184, v185
; __device__ __forceinline__ unsigned cvt_pk_bf16(float lo, float hi) { unsigned r; asm volatile("v_cvt_pk_bf16_f32 %0, %1, %2" : "=v"(r) : "v"(lo), "v"(hi)); return r; }
;     __device__ __forceinline__ void operator()(const Acc& acc, const Unit& u, int wr, int wc, int fr, int fq) const {
;     ...
;                 for (int bj = 0; bj < 2; ++bj) {
;                     const f32x4 o0 = R[m][bj][0] + acc[ai][bj][m][0] * sc, o1 = R[m][bj][1] + acc[ai][bj][m][1] * sc;
;                     if (ok) {
;                         *(f32x4*)(dst + bj * 32) = o0; *(f32x4*)(dst + bj * 32 + 4) = o1;
;                         if (MODE != 2) { part += ((o0[0] * o0[0] + o0[1] * o0[1]) + (o0[2] * o0[2] + o0[3] * o0[3])) + ((o1[0] * o1[0] + o1[1] * o1[1]) + (o1[2] * o1[2] + o1[3] * o1[3]));
;                             u32x4 w; w.x = cvt_pk_bf16(o0[0], o0[1]); w.y = cvt_pk_bf16(o0[2], o0[3]); w.z = cvt_pk_bf16(o1[0], o1[1]); w.w = cvt_pk_bf16(o1[2], o1[3]);
;                             *(u32x4*)(xb + (size_t)row * DM + colb + bj * 32) = w; }
.LBB0_553:
	s_or_b64 exec, exec, s[0:1]
	s_and_saveexec_b64 s[0:1], s[16:17]
	s_cbranch_execz .LBB0_555
	s_waitcnt vmcnt(0)
	v_pk_fma_f32 v[116:117], v[116:117], 0.5, v[180:181] op_sel_hi:[1,0,1]
	v_pk_fma_f32 v[112:113], v[112:113], 0.5, v[176:177] op_sel_hi:[1,0,1]
	v_pk_fma_f32 v[118:119], v[118:119], 0.5, v[182:183] op_sel_hi:[1,0,1]
	v_pk_fma_f32 v[114:115], v[114:115], 0.5, v[178:179] op_sel_hi:[1,0,1]
	v_mov_b32_e32 v122, v113
	v_mov_b32_e32 v123, v117
	v_mov_b32_e32 v120, v112
	v_mov_b32_e32 v121, v116
	v_pk_mul_f32 v[122:123], v[122:123], v[122:123]
	v_mov_b32_e32 v124, v115
	v_mov_b32_e32 v125, v119
	v_pk_fma_f32 v[120:121], v[120:121], v[120:121], v[122:123]
	v_mov_b32_e32 v122, v114
	v_mov_b32_e32 v123, v118
	v_pk_mul_f32 v[124:125], v[124:125], v[124:125]
	global_store_dwordx4 v[232:233], v[112:115], off offset:128 nt
	global_store_dwordx4 v[232:233], v[116:119], off offset:144 nt
	v_pk_fma_f32 v[122:123], v[122:123], v[122:123], v[124:125]
	v_cvt_pk_bf16_f32 v112, v112, v113
	v_cvt_pk_bf16_f32 v113, v114, v115
	v_cvt_pk_bf16_f32 v114, v116, v117
	v_cvt_pk_bf16_f32 v115, v118, v119
	global_store_dwordx4 v[230:231], v[112:115], off offset:64
	v_pk_add_f32 v[120:121], v[120:121], v[122:123]
	s_nop 0
	v_add_f32_e32 v120, v120, v121
	v_add_f32_e32 v219, v120, v219

; __device__ __forceinline__ unsigned cvt_pk_bf16(float lo, float hi) { unsigned r; asm volatile("v_cvt_pk_bf16_f32 %0, %1, %2" : "=v"(r) : "v"(lo), "v"(hi)); return r; }
;     __device__ __forceinline__ void operator()(const Acc& acc, const Unit& u, int wr, int wc, int fr, int fq) const {
;     ...
;             for (int m = 0; m < 4; ++m) {
;                 const int row = u.pm * 256 + ai * 128 + wr * 64 + m * 16 + fr;
;                 const bool ok = row < MREAL; const int rr = ok ? row : 0;
;                 float* dst = ((MODE == 2) ? y_row(P, rr) : x1_row(P, rr)) + colb;
;                 float part = 0.f;
; #pragma unroll
;                 for (int bj = 0; bj < 2; ++bj) {
;                     const f32x4 o0 = R[m][bj][0] + acc[ai][bj][m][0] * sc, o1 = R[m][bj][1] + acc[ai][bj][m][1] * sc;
;                     if (ok) {
;                         *(f32x4*)(dst + bj * 32) = o0; *(f32x4*)(dst + bj * 32 + 4) = o1;
;                         if (MODE != 2) { part += ((o0[0] * o0[0] + o0[1] * o0[1]) + (o0[2] * o0[2] + o0[3] * o0[3])) + ((o1[0] * o1[0] + o1[1] * o1[1]) + (o1[2] * o1[2] + o1[3] * o1[3]));
;                             u32x4 w; w.x = cvt_pk_bf16(o0[0], o0[1]); w.y = cvt_pk_bf16(o0[2], o0[3]); w.z = cvt_pk_bf16(o1[0], o1[1]); w.w = cvt_pk_bf16(o1[2], o1[3]);
;                             *(u32x4*)(xb + (size_t)row * DM + colb + bj * 32) = w; }
.LBB0_557:
	s_or_b64 exec, exec, s[0:1]
	v_readlane_b32 s64, v254, 1
	v_readlane_b32 s66, v254, 3
	v_readlane_b32 s67, v254, 4
	v_readlane_b32 s70, v254, 7
	v_readlane_b32 s71, v254, 8
	s_mov_b64 s[66:67], s[70:71]
	v_mov_b32_e32 v112, s58
	s_waitcnt lgkmcnt(0)
	v_mov_b32_e32 v113, s67
	v_cndmask_b32_e64 v113, v112, v113, s[18:19]
	v_mov_b32_e32 v112, s57
	v_mov_b32_e32 v114, s66
	v_cndmask_b32_e64 v112, v112, v114, s[18:19]
	v_lshl_add_u64 v[112:113], v[112:113], 0, v[228:229]
	v_ashrrev_i32_e32 v225, 31, v224
	v_readlane_b32 s0, v254, 49
	v_lshl_add_u64 v[114:115], v[212:213], 2, v[112:113]
	v_lshlrev_b64 v[112:113], 11, v[224:225]
	v_readlane_b32 s1, v254, 50
	v_mov_b32_e32 v116, 0
	v_readlane_b32 s65, v254, 2
	v_lshl_add_u64 v[112:113], s[0:1], 0, v[112:113]
	v_lshl_add_u64 v[112:113], v[212:213], 1, v[112:113]
	v_readlane_b32 s68, v254, 5
	v_readlane_b32 s69, v254, 6
	s_and_saveexec_b64 s[0:1], s[12:13]
	s_cbranch_execz .LBB0_559
	v_pk_fma_f32 v[108:109], v[108:109], 0.5, v[172:173] op_sel_hi:[1,0,1]
	v_pk_fma_f32 v[104:105], v[104:105], 0.5, v[168:169] op_sel_hi:[1,0,1]
	v_pk_fma_f32 v[110:111], v[110:111], 0.5, v[174:175] op_sel_hi:[1,0,1]
	v_pk_fma_f32 v[106:107], v[106:107], 0.5, v[170:171] op_sel_hi:[1,0,1]
	v_mov_b32_e32 v118, v105
	v_mov_b32_e32 v119, v109
	v_mov_b32_e32 v116, v104
	v_mov_b32_e32 v117, v108
	v_pk_mul_f32 v[118:119], v[118:119], v[118:119]
	v_mov_b32_e32 v120, v107
	v_mov_b32_e32 v121, v111
	v_pk_fma_f32 v[116:117], v[116:117], v[116:117], v[118:119]
	v_mov_b32_e32 v118, v106
	v_mov_b32_e32 v119, v110
	v_pk_mul_f32 v[120:121], v[120:121], v[120:121]
	global_store_dwordx4 v[114:115], v[104:107], off nt
	global_store_dwordx4 v[114:115], v[108:111], off offset:16 nt
	v_pk_fma_f32 v[118:119], v[118:119], v[118:119], v[120:121]
	v_cvt_pk_bf16_f32 v104, v104, v105
	v_cvt_pk_bf16_f32 v105, v106, v107
	v_cvt_pk_bf16_f32 v106, v108, v109
	v_cvt_pk_bf16_f32 v107, v110, v111
	global_store_dwordx4 v[112:113], v[104:107], off
	v_pk_add_f32 v[116:117], v[116:117], v[118:119]
	s_nop 0
	v_add_f32_e32 v116, v116, v117
.LBB0_559:
	s_or_b64 exec, exec, s[0:1]
	s_and_saveexec_b64 s[0:1], s[12:13]
	s_cbranch_execz .LBB0_561
	v_pk_fma_f32 v[100:101], v[100:101], 0.5, v[164:165] op_sel_hi:[1,0,1]
	v_pk_fma_f32 v[96:97], v[96:97], 0.5, v[160:161] op_sel_hi:[1,0,1]
	v_pk_fma_f32 v[102:103], v[102:103], 0.5, v[166:167] op_sel_hi:[1,0,1]
	v_pk_fma_f32 v[98:99], v[98:99], 0.5, v[162:163] op_sel_hi:[1,0,1]
	v_mov_b32_e32 v106, v97
	v_mov_b32_e32 v107, v101
	v_mov_b32_e32 v104, v96
	v_mov_b32_e32 v105, v100
	v_pk_mul_f32 v[106:107], v[106:107], v[106:107]
	v_mov_b32_e32 v108, v99
	v_mov_b32_e32 v109, v103
	v_pk_fma_f32 v[104:105], v[104:105], v[104:105], v[106:107]
	v_mov_b32_e32 v106, v98
	v_mov_b32_e32 v107, v102
	v_pk_mul_f32 v[108:109], v[108:109], v[108:109]
	global_store_dwordx4 v[114:115], v[96:99], off offset:128 nt
	global_store_dwordx4 v[114:115], v[100:103], off offset:144 nt
	v_pk_fma_f32 v[106:107], v[106:107], v[106:107], v[108:109]
	v_cvt_pk_bf16_f32 v96, v96, v97
	v_cvt_pk_bf16_f32 v97, v98, v99
	v_cvt_pk_bf16_f32 v98, v100, v101
	v_cvt_pk_bf16_f32 v99, v102, v103
	global_store_dwordx4 v[112:113], v[96:99], off offset:64
	v_pk_add_f32 v[104:105], v[104:105], v[106:107]
	s_nop 0
	v_add_f32_e32 v104, v104, v105
	v_add_f32_e32 v116, v104, v116

; __device__ __forceinline__ unsigned cvt_pk_bf16(float lo, float hi) { unsigned r; asm volatile("v_cvt_pk_bf16_f32 %0, %1, %2" : "=v"(r) : "v"(lo), "v"(hi)); return r; }
;     __device__ __forceinline__ void operator()(const Acc& acc, const Unit& u, int wr, int wc, int fr, int fq) const {
;     ...
;             for (int m = 0; m < 4; ++m) {
;                 const int row = u.pm * 256 + ai * 128 + wr * 64 + m * 16 + fr;
;                 const bool ok = row < MREAL; const int rr = ok ? row : 0;
;                 float* dst = ((MODE == 2) ? y_row(P, rr) : x1_row(P, rr)) + colb;
;                 float part = 0.f;
; #pragma unroll
;                 for (int bj = 0; bj < 2; ++bj) {
;                     const f32x4 o0 = R[m][bj][0] + acc[ai][bj][m][0] * sc, o1 = R[m][bj][1] + acc[ai][bj][m][1] * sc;
;                     if (ok) {
;                         *(f32x4*)(dst + bj * 32) = o0; *(f32x4*)(dst + bj * 32 + 4) = o1;
;                         if (MODE != 2) { part += ((o0[0] * o0[0] + o0[1] * o0[1]) + (o0[2] * o0[2] + o0[3] * o0[3])) + ((o1[0] * o1[0] + o1[1] * o1[1]) + (o1[2] * o1[2] + o1[3] * o1[3]));
;                             u32x4 w; w.x = cvt_pk_bf16(o0[0], o0[1]); w.y = cvt_pk_bf16(o0[2], o0[3]); w.z = cvt_pk_bf16(o1[0], o1[1]); w.w = cvt_pk_bf16(o1[2], o1[3]);
;                             *(u32x4*)(xb + (size_t)row * DM + colb + bj * 32) = w; }
.LBB0_563:
	s_or_b64 exec, exec, s[0:1]
	v_readlane_b32 s64, v254, 1
	v_readlane_b32 s70, v254, 7
	v_readlane_b32 s71, v254, 8
	s_mov_b64 s[18:19], s[70:71]
	v_mov_b32_e32 v96, s58
	s_waitcnt lgkmcnt(0)
	v_mov_b32_e32 v97, s19
	v_cndmask_b32_e64 v97, v96, v97, s[14:15]
	v_mov_b32_e32 v96, s57
	v_mov_b32_e32 v98, s18
	v_cndmask_b32_e64 v96, v96, v98, s[14:15]
	v_lshl_add_u64 v[96:97], v[96:97], 0, v[226:227]
	v_ashrrev_i32_e32 v221, 31, v220
	v_readlane_b32 s0, v254, 49
	v_lshl_add_u64 v[98:99], v[212:213], 2, v[96:97]
	v_lshlrev_b64 v[96:97], 11, v[220:221]
	v_readlane_b32 s1, v254, 50
	v_mov_b32_e32 v100, 0
	v_readlane_b32 s65, v254, 2
	v_lshl_add_u64 v[96:97], s[0:1], 0, v[96:97]
	v_lshl_add_u64 v[96:97], v[212:213], 1, v[96:97]
	v_readlane_b32 s66, v254, 3
	v_readlane_b32 s67, v254, 4
	v_readlane_b32 s68, v254, 5
	v_readlane_b32 s69, v254, 6
	s_and_saveexec_b64 s[0:1], s[8:9]
	s_cbranch_execz .LBB0_565
	v_pk_fma_f32 v[92:93], v[92:93], 0.5, v[156:157] op_sel_hi:[1,0,1]
	v_pk_fma_f32 v[88:89], v[88:89], 0.5, v[152:153] op_sel_hi:[1,0,1]
	v_pk_fma_f32 v[94:95], v[94:95], 0.5, v[158:159] op_sel_hi:[1,0,1]
	v_pk_fma_f32 v[90:91], v[90:91], 0.5, v[154:155] op_sel_hi:[1,0,1]
	v_mov_b32_e32 v102, v89
	v_mov_b32_e32 v103, v93
	v_mov_b32_e32 v100, v88
	v_mov_b32_e32 v101, v92
	v_pk_mul_f32 v[102:103], v[102:103], v[102:103]
	v_mov_b32_e32 v104, v91
	v_mov_b32_e32 v105, v95
	v_pk_fma_f32 v[100:101], v[100:101], v[100:101], v[102:103]
	v_mov_b32_e32 v102, v90
	v_mov_b32_e32 v103, v94
	v_pk_mul_f32 v[104:105], v[104:105], v[104:105]
	global_store_dwordx4 v[98:99], v[88:91], off nt
	global_store_dwordx4 v[98:99], v[92:95], off offset:16 nt
	v_pk_fma_f32 v[102:103], v[102:103], v[102:103], v[104:105]
	v_cvt_pk_bf16_f32 v88, v88, v89
	v_cvt_pk_bf16_f32 v89, v90, v91
	v_cvt_pk_bf16_f32 v90, v92, v93
	v_cvt_pk_bf16_f32 v91, v94, v95
	global_store_dwordx4 v[96:97], v[88:91], off
	v_pk_add_f32 v[100:101], v[100:101], v[102:103]
	s_nop 0
	v_add_f32_e32 v100, v100, v101
.LBB0_565:
	s_or_b64 exec, exec, s[0:1]
	s_and_saveexec_b64 s[0:1], s[8:9]
	s_cbranch_execz .LBB0_567
	v_pk_fma_f32 v[84:85], v[84:85], 0.5, v[148:149] op_sel_hi:[1,0,1]
	v_pk_fma_f32 v[80:81], v[80:81], 0.5, v[144:145] op_sel_hi:[1,0,1]
	v_pk_fma_f32 v[86:87], v[86:87], 0.5, v[150:151] op_sel_hi:[1,0,1]
	v_pk_fma_f32 v[82:83], v[82:83], 0.5, v[146:147] op_sel_hi:[1,0,1]
	v_mov_b32_e32 v90, v81
	v_mov_b32_e32 v91, v85
	v_mov_b32_e32 v88, v80
	v_mov_b32_e32 v89, v84
	v_pk_mul_f32 v[90:91], v[90:91], v[90:91]
	v_mov_b32_e32 v92, v83
	v_mov_b32_e32 v93, v87
	v_pk_fma_f32 v[88:89], v[88:89], v[88:89], v[90:91]
	v_mov_b32_e32 v90, v82
	v_mov_b32_e32 v91, v86
	v_pk_mul_f32 v[92:93], v[92:93], v[92:93]
	global_store_dwordx4 v[98:99], v[80:83], off offset:128 nt
	global_store_dwordx4 v[98:99], v[84:87], off offset:144 nt
	v_pk_fma_f32 v[90:91], v[90:91], v[90:91], v[92:93]
	v_cvt_pk_bf16_f32 v80, v80, v81
	v_cvt_pk_bf16_f32 v81, v82, v83
	v_cvt_pk_bf16_f32 v82, v84, v85
	v_cvt_pk_bf16_f32 v83, v86, v87
	global_store_dwordx4 v[96:97], v[80:83], off offset:64
	v_pk_add_f32 v[88:89], v[88:89], v[90:91]
	s_nop 0
	v_add_f32_e32 v88, v88, v89
	v_add_f32_e32 v100, v88, v100

; __device__ __forceinline__ unsigned cvt_pk_bf16(float lo, float hi) { unsigned r; asm volatile("v_cvt_pk_bf16_f32 %0, %1, %2" : "=v"(r) : "v"(lo), "v"(hi)); return r; }
;     __device__ __forceinline__ void operator()(const Acc& acc, const Unit& u, int wr, int wc, int fr, int fq) const {
;     ...
;             for (int m = 0; m < 4; ++m) {
;                 const int row = u.pm * 256 + ai * 128 + wr * 64 + m * 16 + fr;
;                 const bool ok = row < MREAL; const int rr = ok ? row : 0;
;                 float* dst = ((MODE == 2) ? y_row(P, rr) : x1_row(P, rr)) + colb;
;                 float part = 0.f;
; #pragma unroll
;                 for (int bj = 0; bj < 2; ++bj) {
;                     const f32x4 o0 = R[m][bj][0] + acc[ai][bj][m][0] * sc, o1 = R[m][bj][1] + acc[ai][bj][m][1] * sc;
;                     if (ok) {
;                         *(f32x4*)(dst + bj * 32) = o0; *(f32x4*)(dst + bj * 32 + 4) = o1;
;                         if (MODE != 2) { part += ((o0[0] * o0[0] + o0[1] * o0[1]) + (o0[2] * o0[2] + o0[3] * o0[3])) + ((o1[0] * o1[0] + o1[1] * o1[1]) + (o1[2] * o1[2] + o1[3] * o1[3]));
;                             u32x4 w; w.x = cvt_pk_bf16(o0[0], o0[1]); w.y = cvt_pk_bf16(o0[2], o0[3]); w.z = cvt_pk_bf16(o1[0], o1[1]); w.w = cvt_pk_bf16(o1[2], o1[3]);
;                             *(u32x4*)(xb + (size_t)row * DM + colb + bj * 32) = w; }
.LBB0_569:
	s_or_b64 exec, exec, s[0:1]
	v_readlane_b32 s12, v254, 1
	v_readlane_b32 s14, v254, 3
	v_readlane_b32 s15, v254, 4
	v_readlane_b32 s18, v254, 7
	v_readlane_b32 s19, v254, 8
	s_mov_b64 s[14:15], s[18:19]
	v_mov_b32_e32 v80, s58
	s_waitcnt lgkmcnt(0)
	v_mov_b32_e32 v81, s15
	v_cndmask_b32_e64 v81, v80, v81, s[10:11]
	v_mov_b32_e32 v80, s57
	v_mov_b32_e32 v82, s14
	v_cndmask_b32_e64 v80, v80, v82, s[10:11]
	v_lshl_add_u64 v[80:81], v[80:81], 0, v[222:223]
	v_ashrrev_i32_e32 v219, 31, v218
	v_readlane_b32 s0, v254, 49
	v_lshl_add_u64 v[82:83], v[212:213], 2, v[80:81]
	v_lshlrev_b64 v[80:81], 11, v[218:219]
	v_readlane_b32 s1, v254, 50
	v_mov_b32_e32 v84, 0
	v_readlane_b32 s13, v254, 2
	v_lshl_add_u64 v[80:81], s[0:1], 0, v[80:81]
	v_lshl_add_u64 v[80:81], v[212:213], 1, v[80:81]
	v_readlane_b32 s16, v254, 5
	v_readlane_b32 s17, v254, 6
	s_and_saveexec_b64 s[0:1], vcc
	s_cbranch_execz .LBB0_571
	v_pk_fma_f32 v[76:77], v[76:77], 0.5, v[140:141] op_sel_hi:[1,0,1]
	v_pk_fma_f32 v[72:73], v[72:73], 0.5, v[136:137] op_sel_hi:[1,0,1]
	v_pk_fma_f32 v[78:79], v[78:79], 0.5, v[142:143] op_sel_hi:[1,0,1]
	v_pk_fma_f32 v[74:75], v[74:75], 0.5, v[138:139] op_sel_hi:[1,0,1]
	v_mov_b32_e32 v86, v73
	v_mov_b32_e32 v87, v77
	v_mov_b32_e32 v84, v72
	v_mov_b32_e32 v85, v76
	v_pk_mul_f32 v[86:87], v[86:87], v[86:87]
	v_mov_b32_e32 v88, v75
	v_mov_b32_e32 v89, v79
	v_pk_fma_f32 v[84:85], v[84:85], v[84:85], v[86:87]
	v_mov_b32_e32 v86, v74
	v_mov_b32_e32 v87, v78
	v_pk_mul_f32 v[88:89], v[88:89], v[88:89]
	global_store_dwordx4 v[82:83], v[72:75], off nt
	global_store_dwordx4 v[82:83], v[76:79], off offset:16 nt
	v_pk_fma_f32 v[86:87], v[86:87], v[86:87], v[88:89]
	v_cvt_pk_bf16_f32 v72, v72, v73
	v_cvt_pk_bf16_f32 v73, v74, v75
	v_cvt_pk_bf16_f32 v74, v76, v77
	v_cvt_pk_bf16_f32 v75, v78, v79
	global_store_dwordx4 v[80:81], v[72:75], off
	v_pk_add_f32 v[84:85], v[84:85], v[86:87]
	s_nop 0
	v_add_f32_e32 v84, v84, v85
.LBB0_571:
	s_or_b64 exec, exec, s[0:1]
	s_and_saveexec_b64 s[0:1], vcc
	s_cbranch_execz .LBB0_573
	v_pk_fma_f32 v[68:69], v[68:69], 0.5, v[132:133] op_sel_hi:[1,0,1]
	v_pk_fma_f32 v[64:65], v[64:65], 0.5, v[128:129] op_sel_hi:[1,0,1]
	v_pk_fma_f32 v[70:71], v[70:71], 0.5, v[134:135] op_sel_hi:[1,0,1]
	v_pk_fma_f32 v[66:67], v[66:67], 0.5, v[130:131] op_sel_hi:[1,0,1]
	v_mov_b32_e32 v74, v65
	v_mov_b32_e32 v75, v69
	v_mov_b32_e32 v72, v64
	v_mov_b32_e32 v73, v68
	v_pk_mul_f32 v[74:75], v[74:75], v[74:75]
	v_mov_b32_e32 v76, v67
	v_mov_b32_e32 v77, v71
	v_pk_fma_f32 v[72:73], v[72:73], v[72:73], v[74:75]
	v_mov_b32_e32 v74, v66
	v_mov_b32_e32 v75, v70
	v_pk_mul_f32 v[76:77], v[76:77], v[76:77]
	global_store_dwordx4 v[82:83], v[64:67], off offset:128 nt
	global_store_dwordx4 v[82:83], v[68:71], off offset:144 nt
	v_pk_fma_f32 v[74:75], v[74:75], v[74:75], v[76:77]
	v_cvt_pk_bf16_f32 v64, v64, v65
	v_cvt_pk_bf16_f32 v65, v66, v67
	v_cvt_pk_bf16_f32 v66, v68, v69
	v_cvt_pk_bf16_f32 v67, v70, v71
	global_store_dwordx4 v[80:81], v[64:67], off offset:64
	v_pk_add_f32 v[72:73], v[72:73], v[74:75]
	s_nop 0
	v_add_f32_e32 v72, v72, v73
	v_add_f32_e32 v84, v72, v84

; __device__ __forceinline__ unsigned cvt_pk_bf16(float lo, float hi) { unsigned r; asm volatile("v_cvt_pk_bf16_f32 %0, %1, %2" : "=v"(r) : "v"(lo), "v"(hi)); return r; }
; #define SCHED_BAR() __builtin_amdgcn_sched_barrier(0)
;     __device__ __forceinline__ void operator()(const Acc& acc, const Unit& u, int wr, int wc, int fr, int fq) const {
;     ...
;         for (int ai = 0; ai < 2; ++ai) {
;             f32x4 R[4][2][2];
; #pragma unroll
;             for (int m = 0; m < 4; ++m) {
;                 const int row = u.pm * 256 + ai * 128 + wr * 64 + m * 16 + fr; const int rr = row < MREAL ? row : 0;
;                 const float* res = ((MODE == 0) ? xin_row(P, rr) : (const float*)x1_row(P, rr)) + colb;
; #pragma unroll
;                 for (int bj = 0; bj < 2; ++bj)
; #pragma unroll
;                     for (int n = 0; n < 2; ++n) R[m][bj][n] = *(const f32x4*)(res + bj * 32 + n * 4);
;             }
;             SCHED_BAR();
; #pragma unroll
;             for (int m = 0; m < 4; ++m) {
;                 const int row = u.pm * 256 + ai * 128 + wr * 64 + m * 16 + fr;
;                 const bool ok = row < MREAL; const int rr = ok ? row : 0;
;                 float* dst = ((MODE == 2) ? y_row(P, rr) : x1_row(P, rr)) + colb;
;                 float part = 0.f;
; #pragma unroll
;                 for (int bj = 0; bj < 2; ++bj) {
;                     const f32x4 o0 = R[m][bj][0] + acc[ai][bj][m][0] * sc, o1 = R[m][bj][1] + acc[ai][bj][m][1] * sc;
;                     if (ok) {
;                         *(f32x4*)(dst + bj * 32) = o0; *(f32x4*)(dst + bj * 32 + 4) = o1;
;                         if (MODE != 2) { part += ((o0[0] * o0[0] + o0[1] * o0[1]) + (o0[2] * o0[2] + o0[3] * o0[3])) + ((o1[0] * o1[0] + o1[1] * o1[1]) + (o1[2] * o1[2] + o1[3] * o1[3]));
;                             u32x4 w; w.x = cvt_pk_bf16(o0[0], o0[1]); w.y = cvt_pk_bf16(o0[2], o0[3]); w.z = cvt_pk_bf16(o1[0], o1[1]); w.w = cvt_pk_bf16(o1[2], o1[3]);
;                             *(u32x4*)(xb + (size_t)row * DM + colb + bj * 32) = w; }
.LBB0_575:
	s_or_b64 exec, exec, s[0:1]
	v_add_u32_e32 v138, 0x80, v216
	v_cmp_gt_i32_e64 s[16:17], s61, v138
	v_readlane_b32 s64, v254, 19
	v_readlane_b32 s65, v254, 20
	v_cndmask_b32_e64 v64, 0, v138, s[16:17]
	v_add_u32_e32 v66, 0xffff8000, v64
	s_waitcnt lgkmcnt(0)
	v_ashrrev_i32_e32 v65, 31, v64
	v_cmp_gt_i32_e64 s[0:1], s53, v64
	v_readlane_b32 s66, v254, 21
	v_readlane_b32 s67, v254, 22
	v_cndmask_b32_e64 v65, 0, v65, s[0:1]
	v_cndmask_b32_e64 v64, v66, v64, s[0:1]
	v_mov_b32_e32 v68, s67
	v_mov_b32_e32 v69, s65
	v_mov_b32_e32 v70, s66
	v_mov_b32_e32 v71, s64
	v_cndmask_b32_e64 v67, v68, v69, s[0:1]
	v_cndmask_b32_e64 v66, v70, v71, s[0:1]
	v_lshlrev_b64 v[142:143], 12, v[64:65]
	v_lshl_add_u64 v[64:65], v[66:67], 0, v[142:143]
	v_add_u32_e32 v134, 0x90, v216
	v_lshl_add_u64 v[64:65], v[64:65], 0, v[214:215]
	v_cmp_gt_i32_e64 s[12:13], s61, v134
	global_load_dwordx4 v[124:127], v[64:65], off offset:16 nt
	global_load_dwordx4 v[120:123], v[64:65], off nt
	global_load_dwordx4 v[116:119], v[64:65], off offset:144 nt
	global_load_dwordx4 v[112:115], v[64:65], off offset:128 nt
	v_cndmask_b32_e64 v64, 0, v134, s[12:13]
	v_add_u32_e32 v66, 0xffff8000, v64
	v_ashrrev_i32_e32 v65, 31, v64
	v_cmp_gt_i32_e64 s[18:19], s53, v64
	v_add_u32_e32 v130, 0xa0, v216
	v_cmp_gt_i32_e64 s[8:9], s61, v130
	v_cndmask_b32_e64 v65, 0, v65, s[18:19]
	v_cndmask_b32_e64 v64, v66, v64, s[18:19]
	v_cndmask_b32_e64 v67, v68, v69, s[18:19]
	v_cndmask_b32_e64 v66, v70, v71, s[18:19]
	v_lshlrev_b64 v[140:141], 12, v[64:65]
	v_lshl_add_u64 v[64:65], v[66:67], 0, v[140:141]
	v_lshl_add_u64 v[64:65], v[64:65], 0, v[214:215]
	global_load_dwordx4 v[108:111], v[64:65], off offset:16 nt
	global_load_dwordx4 v[104:107], v[64:65], off nt
	global_load_dwordx4 v[100:103], v[64:65], off offset:144 nt
	global_load_dwordx4 v[96:99], v[64:65], off offset:128 nt
	v_cndmask_b32_e64 v64, 0, v130, s[8:9]
	v_add_u32_e32 v66, 0xffff8000, v64
	v_ashrrev_i32_e32 v65, 31, v64
	v_cmp_gt_i32_e64 s[14:15], s53, v64
	v_add_u32_e32 v128, 0xb0, v216
	v_cmp_gt_i32_e32 vcc, s61, v128
	v_cndmask_b32_e64 v65, 0, v65, s[14:15]
	v_cndmask_b32_e64 v64, v66, v64, s[14:15]
	v_cndmask_b32_e64 v67, v68, v69, s[14:15]
	v_cndmask_b32_e64 v66, v70, v71, s[14:15]
	v_lshlrev_b64 v[136:137], 12, v[64:65]
	v_lshl_add_u64 v[64:65], v[66:67], 0, v[136:137]
	v_lshl_add_u64 v[64:65], v[64:65], 0, v[214:215]
	global_load_dwordx4 v[92:95], v[64:65], off offset:16 nt
	global_load_dwordx4 v[88:91], v[64:65], off nt
	global_load_dwordx4 v[84:87], v[64:65], off offset:144 nt
	global_load_dwordx4 v[80:83], v[64:65], off offset:128 nt
	v_cndmask_b32_e32 v64, 0, v128, vcc
	v_add_u32_e32 v66, 0xffff8000, v64
	v_ashrrev_i32_e32 v65, 31, v64
	v_cmp_gt_i32_e64 s[10:11], s53, v64
	v_readlane_b32 s68, v254, 23
	v_readlane_b32 s69, v254, 24
	v_cndmask_b32_e64 v65, 0, v65, s[10:11]
	v_cndmask_b32_e64 v64, v66, v64, s[10:11]
	v_cndmask_b32_e64 v67, v68, v69, s[10:11]
	v_cndmask_b32_e64 v66, v70, v71, s[10:11]
	v_lshlrev_b64 v[132:133], 12, v[64:65]
	v_lshl_add_u64 v[64:65], v[66:67], 0, v[132:133]
	v_lshl_add_u64 v[64:65], v[64:65], 0, v[214:215]
	global_load_dwordx4 v[76:79], v[64:65], off offset:16 nt
	global_load_dwordx4 v[72:75], v[64:65], off nt
	global_load_dwordx4 v[68:71], v[64:65], off offset:144 nt
	s_nop 0
	global_load_dwordx4 v[64:67], v[64:65], off offset:128 nt
	v_readlane_b32 s70, v254, 25
	v_readlane_b32 s71, v254, 26
	v_readlane_b32 s72, v254, 27
	v_readlane_b32 s73, v254, 28
	v_readlane_b32 s74, v254, 29
	v_readlane_b32 s75, v254, 30
	v_readlane_b32 s76, v254, 31
	v_readlane_b32 s77, v254, 32
	v_readlane_b32 s78, v254, 33
	v_readlane_b32 s79, v254, 34
	v_readlane_b32 s64, v254, 1
	v_readlane_b32 s66, v254, 3
	v_readlane_b32 s67, v254, 4
	v_readlane_b32 s70, v254, 7
	v_readlane_b32 s71, v254, 8
	s_mov_b64 s[66:67], s[70:71]
	v_mov_b32_e32 v129, s58
	v_mov_b32_e32 v131, s67
	v_cndmask_b32_e64 v145, v129, v131, s[0:1]
	v_mov_b32_e32 v129, s57
	v_mov_b32_e32 v131, s66
	v_cndmask_b32_e64 v144, v129, v131, s[0:1]
	v_lshl_add_u64 v[142:143], v[144:145], 0, v[142:143]
	v_ashrrev_i32_e32 v139, 31, v138
	v_readlane_b32 s0, v254, 49
	v_lshl_add_u64 v[144:145], v[142:143], 0, v[214:215]
	v_lshlrev_b64 v[142:143], 11, v[138:139]
	v_readlane_b32 s1, v254, 50
	v_mov_b32_e32 v129, 0
	v_readlane_b32 s65, v254, 2
	v_lshl_add_u64 v[142:143], s[0:1], 0, v[142:143]
	v_lshl_add_u64 v[142:143], v[212:213], 1, v[142:143]
	v_readlane_b32 s68, v254, 5
	v_readlane_b32 s69, v254, 6
	s_and_saveexec_b64 s[0:1], s[16:17]
	s_cbranch_execz .LBB0_577
	s_waitcnt vmcnt(15)
	v_pk_fma_f32 v[60:61], v[60:61], 0.5, v[124:125] op_sel_hi:[1,0,1]
	s_waitcnt vmcnt(14)
	v_pk_fma_f32 v[56:57], v[56:57], 0.5, v[120:121] op_sel_hi:[1,0,1]
	v_pk_fma_f32 v[62:63], v[62:63], 0.5, v[126:127] op_sel_hi:[1,0,1]
	v_pk_fma_f32 v[58:59], v[58:59], 0.5, v[122:123] op_sel_hi:[1,0,1]
	v_mov_b32_e32 v122, v57
	v_mov_b32_e32 v123, v61
	v_mov_b32_e32 v120, v56
	v_mov_b32_e32 v121, v60
	v_pk_mul_f32 v[122:123], v[122:123], v[122:123]
	v_mov_b32_e32 v124, v59
	v_mov_b32_e32 v125, v63
	v_pk_fma_f32 v[120:121], v[120:121], v[120:121], v[122:123]
	v_mov_b32_e32 v122, v58
	v_mov_b32_e32 v123, v62
	v_pk_mul_f32 v[124:125], v[124:125], v[124:125]
	global_store_dwordx4 v[144:145], v[56:59], off nt
	global_store_dwordx4 v[144:145], v[60:63], off offset:16 nt
	v_pk_fma_f32 v[122:123], v[122:123], v[122:123], v[124:125]
	v_cvt_pk_bf16_f32 v56, v56, v57
	v_cvt_pk_bf16_f32 v57, v58, v59
	v_cvt_pk_bf16_f32 v58, v60, v61
	v_cvt_pk_bf16_f32 v59, v62, v63
	global_store_dwordx4 v[142:143], v[56:59], off
	v_pk_add_f32 v[120:121], v[120:121], v[122:123]
	s_nop 0
	v_add_f32_e32 v129, v120, v121
.LBB0_577:
	s_or_b64 exec, exec, s[0:1]
	s_and_saveexec_b64 s[0:1], s[16:17]
	s_cbranch_execz .LBB0_579
	s_waitcnt vmcnt(13)
	v_pk_fma_f32 v[52:53], v[52:53], 0.5, v[116:117] op_sel_hi:[1,0,1]
	s_waitcnt vmcnt(12)
	v_pk_fma_f32 v[48:49], v[48:49], 0.5, v[112:113] op_sel_hi:[1,0,1]
	v_pk_fma_f32 v[54:55], v[54:55], 0.5, v[118:119] op_sel_hi:[1,0,1]
	v_pk_fma_f32 v[50:51], v[50:51], 0.5, v[114:115] op_sel_hi:[1,0,1]
	v_mov_b32_e32 v58, v49
	v_mov_b32_e32 v59, v53
	v_mov_b32_e32 v56, v48
	v_mov_b32_e32 v57, v52
	v_pk_mul_f32 v[58:59], v[58:59], v[58:59]
	v_mov_b32_e32 v60, v51
	v_mov_b32_e32 v61, v55
	v_pk_fma_f32 v[56:57], v[56:57], v[56:57], v[58:59]
	v_mov_b32_e32 v58, v50
	v_mov_b32_e32 v59, v54
	v_pk_mul_f32 v[60:61], v[60:61], v[60:61]
	global_store_dwordx4 v[144:145], v[48:51], off offset:128 nt
	global_store_dwordx4 v[144:145], v[52:55], off offset:144 nt
	v_pk_fma_f32 v[58:59], v[58:59], v[58:59], v[60:61]
	v_cvt_pk_bf16_f32 v48, v48, v49
	v_cvt_pk_bf16_f32 v49, v50, v51
	v_cvt_pk_bf16_f32 v50, v52, v53
	v_cvt_pk_bf16_f32 v51, v54, v55
	global_store_dwordx4 v[142:143], v[48:51], off offset:64
	v_pk_add_f32 v[56:57], v[56:57], v[58:59]
	s_nop 0
	v_add_f32_e32 v56, v56, v57
	v_add_f32_e32 v129, v56, v129

; __device__ __forceinline__ unsigned cvt_pk_bf16(float lo, float hi) { unsigned r; asm volatile("v_cvt_pk_bf16_f32 %0, %1, %2" : "=v"(r) : "v"(lo), "v"(hi)); return r; }
;     __device__ __forceinline__ void operator()(const Acc& acc, const Unit& u, int wr, int wc, int fr, int fq) const {
;     ...
;             for (int m = 0; m < 4; ++m) {
;                 const int row = u.pm * 256 + ai * 128 + wr * 64 + m * 16 + fr;
;                 const bool ok = row < MREAL; const int rr = ok ? row : 0;
;                 float* dst = ((MODE == 2) ? y_row(P, rr) : x1_row(P, rr)) + colb;
;                 float part = 0.f;
; #pragma unroll
;                 for (int bj = 0; bj < 2; ++bj) {
;                     const f32x4 o0 = R[m][bj][0] + acc[ai][bj][m][0] * sc, o1 = R[m][bj][1] + acc[ai][bj][m][1] * sc;
;                     if (ok) {
;                         *(f32x4*)(dst + bj * 32) = o0; *(f32x4*)(dst + bj * 32 + 4) = o1;
;                         if (MODE != 2) { part += ((o0[0] * o0[0] + o0[1] * o0[1]) + (o0[2] * o0[2] + o0[3] * o0[3])) + ((o1[0] * o1[0] + o1[1] * o1[1]) + (o1[2] * o1[2] + o1[3] * o1[3]));
;                             u32x4 w; w.x = cvt_pk_bf16(o0[0], o0[1]); w.y = cvt_pk_bf16(o0[2], o0[3]); w.z = cvt_pk_bf16(o1[0], o1[1]); w.w = cvt_pk_bf16(o1[2], o1[3]);
;                             *(u32x4*)(xb + (size_t)row * DM + colb + bj * 32) = w; }
.LBB0_581:
	s_or_b64 exec, exec, s[0:1]
	v_readlane_b32 s64, v254, 1
	v_readlane_b32 s66, v254, 3
	v_readlane_b32 s67, v254, 4
	v_readlane_b32 s70, v254, 7
	v_readlane_b32 s71, v254, 8
	s_mov_b64 s[66:67], s[70:71]
	v_mov_b32_e32 v48, s58
	s_waitcnt lgkmcnt(0)
	v_mov_b32_e32 v49, s67
	v_cndmask_b32_e64 v49, v48, v49, s[18:19]
	v_mov_b32_e32 v48, s57
	v_mov_b32_e32 v50, s66
	v_cndmask_b32_e64 v48, v48, v50, s[18:19]
	v_lshl_add_u64 v[48:49], v[48:49], 0, v[140:141]
	v_ashrrev_i32_e32 v135, 31, v134
	v_readlane_b32 s0, v254, 49
	v_lshl_add_u64 v[50:51], v[212:213], 2, v[48:49]
	v_lshlrev_b64 v[48:49], 11, v[134:135]
	v_readlane_b32 s1, v254, 50
	v_mov_b32_e32 v52, 0
	v_readlane_b32 s65, v254, 2
	v_lshl_add_u64 v[48:49], s[0:1], 0, v[48:49]
	v_lshl_add_u64 v[48:49], v[212:213], 1, v[48:49]
	v_readlane_b32 s68, v254, 5
	v_readlane_b32 s69, v254, 6
	s_and_saveexec_b64 s[0:1], s[12:13]
	s_cbranch_execz .LBB0_583
	s_waitcnt vmcnt(11)
	v_pk_fma_f32 v[44:45], v[44:45], 0.5, v[108:109] op_sel_hi:[1,0,1]
	s_waitcnt vmcnt(10)
	v_pk_fma_f32 v[40:41], v[40:41], 0.5, v[104:105] op_sel_hi:[1,0,1]
	v_pk_fma_f32 v[46:47], v[46:47], 0.5, v[110:111] op_sel_hi:[1,0,1]
	v_pk_fma_f32 v[42:43], v[42:43], 0.5, v[106:107] op_sel_hi:[1,0,1]
	v_mov_b32_e32 v54, v41
	v_mov_b32_e32 v55, v45
	v_mov_b32_e32 v52, v40
	v_mov_b32_e32 v53, v44
	v_pk_mul_f32 v[54:55], v[54:55], v[54:55]
	v_mov_b32_e32 v56, v43
	v_mov_b32_e32 v57, v47
	v_pk_fma_f32 v[52:53], v[52:53], v[52:53], v[54:55]
	v_mov_b32_e32 v54, v42
	v_mov_b32_e32 v55, v46
	v_pk_mul_f32 v[56:57], v[56:57], v[56:57]
	global_store_dwordx4 v[50:51], v[40:43], off nt
	global_store_dwordx4 v[50:51], v[44:47], off offset:16 nt
	v_pk_fma_f32 v[54:55], v[54:55], v[54:55], v[56:57]
	v_cvt_pk_bf16_f32 v40, v40, v41
	v_cvt_pk_bf16_f32 v41, v42, v43
	v_cvt_pk_bf16_f32 v42, v44, v45
	v_cvt_pk_bf16_f32 v43, v46, v47
	global_store_dwordx4 v[48:49], v[40:43], off
	v_pk_add_f32 v[52:53], v[52:53], v[54:55]
	s_nop 0
	v_add_f32_e32 v52, v52, v53
.LBB0_583:
	s_or_b64 exec, exec, s[0:1]
	s_and_saveexec_b64 s[0:1], s[12:13]
	s_cbranch_execz .LBB0_585
	s_waitcnt vmcnt(9)
	v_pk_fma_f32 v[36:37], v[36:37], 0.5, v[100:101] op_sel_hi:[1,0,1]
	s_waitcnt vmcnt(8)
	v_pk_fma_f32 v[32:33], v[32:33], 0.5, v[96:97] op_sel_hi:[1,0,1]
	v_pk_fma_f32 v[38:39], v[38:39], 0.5, v[102:103] op_sel_hi:[1,0,1]
	v_pk_fma_f32 v[34:35], v[34:35], 0.5, v[98:99] op_sel_hi:[1,0,1]
	v_mov_b32_e32 v42, v33
	v_mov_b32_e32 v43, v37
	v_mov_b32_e32 v40, v32
	v_mov_b32_e32 v41, v36
	v_pk_mul_f32 v[42:43], v[42:43], v[42:43]
	v_mov_b32_e32 v44, v35
	v_mov_b32_e32 v45, v39
	v_pk_fma_f32 v[40:41], v[40:41], v[40:41], v[42:43]
	v_mov_b32_e32 v42, v34
	v_mov_b32_e32 v43, v38
	v_pk_mul_f32 v[44:45], v[44:45], v[44:45]
	global_store_dwordx4 v[50:51], v[32:35], off offset:128 nt
	global_store_dwordx4 v[50:51], v[36:39], off offset:144 nt
	v_pk_fma_f32 v[42:43], v[42:43], v[42:43], v[44:45]
	v_cvt_pk_bf16_f32 v32, v32, v33
	v_cvt_pk_bf16_f32 v33, v34, v35
	v_cvt_pk_bf16_f32 v34, v36, v37
	v_cvt_pk_bf16_f32 v35, v38, v39
	global_store_dwordx4 v[48:49], v[32:35], off offset:64
	v_pk_add_f32 v[40:41], v[40:41], v[42:43]
	s_nop 0
	v_add_f32_e32 v40, v40, v41
	v_add_f32_e32 v52, v40, v52

; __device__ __forceinline__ unsigned cvt_pk_bf16(float lo, float hi) { unsigned r; asm volatile("v_cvt_pk_bf16_f32 %0, %1, %2" : "=v"(r) : "v"(lo), "v"(hi)); return r; }
;     __device__ __forceinline__ void operator()(const Acc& acc, const Unit& u, int wr, int wc, int fr, int fq) const {
;     ...
;             for (int m = 0; m < 4; ++m) {
;                 const int row = u.pm * 256 + ai * 128 + wr * 64 + m * 16 + fr;
;                 const bool ok = row < MREAL; const int rr = ok ? row : 0;
;                 float* dst = ((MODE == 2) ? y_row(P, rr) : x1_row(P, rr)) + colb;
;                 float part = 0.f;
; #pragma unroll
;                 for (int bj = 0; bj < 2; ++bj) {
;                     const f32x4 o0 = R[m][bj][0] + acc[ai][bj][m][0] * sc, o1 = R[m][bj][1] + acc[ai][bj][m][1] * sc;
;                     if (ok) {
;                         *(f32x4*)(dst + bj * 32) = o0; *(f32x4*)(dst + bj * 32 + 4) = o1;
;                         if (MODE != 2) { part += ((o0[0] * o0[0] + o0[1] * o0[1]) + (o0[2] * o0[2] + o0[3] * o0[3])) + ((o1[0] * o1[0] + o1[1] * o1[1]) + (o1[2] * o1[2] + o1[3] * o1[3]));
;                             u32x4 w; w.x = cvt_pk_bf16(o0[0], o0[1]); w.y = cvt_pk_bf16(o0[2], o0[3]); w.z = cvt_pk_bf16(o1[0], o1[1]); w.w = cvt_pk_bf16(o1[2], o1[3]);
;                             *(u32x4*)(xb + (size_t)row * DM + colb + bj * 32) = w; }
.LBB0_587:
	s_or_b64 exec, exec, s[0:1]
	v_readlane_b32 s64, v254, 1
	v_readlane_b32 s70, v254, 7
	v_readlane_b32 s71, v254, 8
	s_mov_b64 s[18:19], s[70:71]
	v_mov_b32_e32 v32, s58
	s_waitcnt lgkmcnt(0)
	v_mov_b32_e32 v33, s19
	v_cndmask_b32_e64 v33, v32, v33, s[14:15]
	v_mov_b32_e32 v32, s57
	v_mov_b32_e32 v34, s18
	v_cndmask_b32_e64 v32, v32, v34, s[14:15]
	v_lshl_add_u64 v[32:33], v[32:33], 0, v[136:137]
	v_ashrrev_i32_e32 v131, 31, v130
	v_readlane_b32 s0, v254, 49
	v_lshl_add_u64 v[34:35], v[212:213], 2, v[32:33]
	v_lshlrev_b64 v[32:33], 11, v[130:131]
	v_readlane_b32 s1, v254, 50
	v_mov_b32_e32 v36, 0
	v_readlane_b32 s65, v254, 2
	v_lshl_add_u64 v[32:33], s[0:1], 0, v[32:33]
	v_lshl_add_u64 v[32:33], v[212:213], 1, v[32:33]
	v_readlane_b32 s66, v254, 3
	v_readlane_b32 s67, v254, 4
	v_readlane_b32 s68, v254, 5
	v_readlane_b32 s69, v254, 6
	s_and_saveexec_b64 s[0:1], s[8:9]
	s_cbranch_execz .LBB0_589
	s_waitcnt vmcnt(7)
	v_pk_fma_f32 v[28:29], v[28:29], 0.5, v[92:93] op_sel_hi:[1,0,1]
	s_waitcnt vmcnt(6)
	v_pk_fma_f32 v[24:25], v[24:25], 0.5, v[88:89] op_sel_hi:[1,0,1]
	v_pk_fma_f32 v[30:31], v[30:31], 0.5, v[94:95] op_sel_hi:[1,0,1]
	v_pk_fma_f32 v[26:27], v[26:27], 0.5, v[90:91] op_sel_hi:[1,0,1]
	v_mov_b32_e32 v38, v25
	v_mov_b32_e32 v39, v29
	v_mov_b32_e32 v36, v24
	v_mov_b32_e32 v37, v28
	v_pk_mul_f32 v[38:39], v[38:39], v[38:39]
	v_mov_b32_e32 v40, v27
	v_mov_b32_e32 v41, v31
	v_pk_fma_f32 v[36:37], v[36:37], v[36:37], v[38:39]
	v_mov_b32_e32 v38, v26
	v_mov_b32_e32 v39, v30
	v_pk_mul_f32 v[40:41], v[40:41], v[40:41]
	global_store_dwordx4 v[34:35], v[24:27], off nt
	global_store_dwordx4 v[34:35], v[28:31], off offset:16 nt
	v_pk_fma_f32 v[38:39], v[38:39], v[38:39], v[40:41]
	v_cvt_pk_bf16_f32 v24, v24, v25
	v_cvt_pk_bf16_f32 v25, v26, v27
	v_cvt_pk_bf16_f32 v26, v28, v29
	v_cvt_pk_bf16_f32 v27, v30, v31
	global_store_dwordx4 v[32:33], v[24:27], off
	v_pk_add_f32 v[36:37], v[36:37], v[38:39]
	s_nop 0
	v_add_f32_e32 v36, v36, v37
.LBB0_589:
	s_or_b64 exec, exec, s[0:1]
	s_and_saveexec_b64 s[0:1], s[8:9]
	s_cbranch_execz .LBB0_591
	s_waitcnt vmcnt(5)
	v_pk_fma_f32 v[20:21], v[20:21], 0.5, v[84:85] op_sel_hi:[1,0,1]
	s_waitcnt vmcnt(4)
	v_pk_fma_f32 v[16:17], v[16:17], 0.5, v[80:81] op_sel_hi:[1,0,1]
	v_pk_fma_f32 v[22:23], v[22:23], 0.5, v[86:87] op_sel_hi:[1,0,1]
	v_pk_fma_f32 v[18:19], v[18:19], 0.5, v[82:83] op_sel_hi:[1,0,1]
	v_mov_b32_e32 v26, v17
	v_mov_b32_e32 v27, v21
	v_mov_b32_e32 v24, v16
	v_mov_b32_e32 v25, v20
	v_pk_mul_f32 v[26:27], v[26:27], v[26:27]
	v_mov_b32_e32 v28, v19
	v_mov_b32_e32 v29, v23
	v_pk_fma_f32 v[24:25], v[24:25], v[24:25], v[26:27]
	v_mov_b32_e32 v26, v18
	v_mov_b32_e32 v27, v22
	v_pk_mul_f32 v[28:29], v[28:29], v[28:29]
	global_store_dwordx4 v[34:35], v[16:19], off offset:128 nt
	global_store_dwordx4 v[34:35], v[20:23], off offset:144 nt
	v_pk_fma_f32 v[26:27], v[26:27], v[26:27], v[28:29]
	v_cvt_pk_bf16_f32 v16, v16, v17
	v_cvt_pk_bf16_f32 v17, v18, v19
	v_cvt_pk_bf16_f32 v18, v20, v21
	v_cvt_pk_bf16_f32 v19, v22, v23
	global_store_dwordx4 v[32:33], v[16:19], off offset:64
	v_pk_add_f32 v[24:25], v[24:25], v[26:27]
	s_nop 0
	v_add_f32_e32 v24, v24, v25
	v_add_f32_e32 v36, v24, v36

; __device__ __forceinline__ unsigned cvt_pk_bf16(float lo, float hi) { unsigned r; asm volatile("v_cvt_pk_bf16_f32 %0, %1, %2" : "=v"(r) : "v"(lo), "v"(hi)); return r; }
;     __device__ __forceinline__ void operator()(const Acc& acc, const Unit& u, int wr, int wc, int fr, int fq) const {
;     ...
;             for (int m = 0; m < 4; ++m) {
;                 const int row = u.pm * 256 + ai * 128 + wr * 64 + m * 16 + fr;
;                 const bool ok = row < MREAL; const int rr = ok ? row : 0;
;                 float* dst = ((MODE == 2) ? y_row(P, rr) : x1_row(P, rr)) + colb;
;                 float part = 0.f;
; #pragma unroll
;                 for (int bj = 0; bj < 2; ++bj) {
;                     const f32x4 o0 = R[m][bj][0] + acc[ai][bj][m][0] * sc, o1 = R[m][bj][1] + acc[ai][bj][m][1] * sc;
;                     if (ok) {
;                         *(f32x4*)(dst + bj * 32) = o0; *(f32x4*)(dst + bj * 32 + 4) = o1;
;                         if (MODE != 2) { part += ((o0[0] * o0[0] + o0[1] * o0[1]) + (o0[2] * o0[2] + o0[3] * o0[3])) + ((o1[0] * o1[0] + o1[1] * o1[1]) + (o1[2] * o1[2] + o1[3] * o1[3]));
;                             u32x4 w; w.x = cvt_pk_bf16(o0[0], o0[1]); w.y = cvt_pk_bf16(o0[2], o0[3]); w.z = cvt_pk_bf16(o1[0], o1[1]); w.w = cvt_pk_bf16(o1[2], o1[3]);
;                             *(u32x4*)(xb + (size_t)row * DM + colb + bj * 32) = w; }
.LBB0_593:
	s_or_b64 exec, exec, s[0:1]
	v_readlane_b32 s12, v254, 1
	v_readlane_b32 s14, v254, 3
	v_readlane_b32 s15, v254, 4
	v_readlane_b32 s18, v254, 7
	v_readlane_b32 s19, v254, 8
	s_mov_b64 s[14:15], s[18:19]
	v_mov_b32_e32 v16, s58
	s_waitcnt lgkmcnt(0)
	v_mov_b32_e32 v17, s15
	v_cndmask_b32_e64 v17, v16, v17, s[10:11]
	v_mov_b32_e32 v16, s57
	v_mov_b32_e32 v18, s14
	v_cndmask_b32_e64 v16, v16, v18, s[10:11]
	v_lshl_add_u64 v[16:17], v[16:17], 0, v[132:133]
	v_ashrrev_i32_e32 v129, 31, v128
	v_readlane_b32 s0, v254, 49
	v_lshl_add_u64 v[18:19], v[212:213], 2, v[16:17]
	v_lshlrev_b64 v[16:17], 11, v[128:129]
	v_readlane_b32 s1, v254, 50
	v_mov_b32_e32 v20, 0
	v_readlane_b32 s13, v254, 2
	v_lshl_add_u64 v[16:17], s[0:1], 0, v[16:17]
	v_lshl_add_u64 v[16:17], v[212:213], 1, v[16:17]
	v_readlane_b32 s16, v254, 5
	v_readlane_b32 s17, v254, 6
	s_and_saveexec_b64 s[0:1], vcc
	s_cbranch_execz .LBB0_595
	s_waitcnt vmcnt(3)
	v_pk_fma_f32 v[12:13], v[12:13], 0.5, v[76:77] op_sel_hi:[1,0,1]
	s_waitcnt vmcnt(2)
	v_pk_fma_f32 v[8:9], v[8:9], 0.5, v[72:73] op_sel_hi:[1,0,1]
	v_pk_fma_f32 v[14:15], v[14:15], 0.5, v[78:79] op_sel_hi:[1,0,1]
	v_pk_fma_f32 v[10:11], v[10:11], 0.5, v[74:75] op_sel_hi:[1,0,1]
	v_mov_b32_e32 v22, v9
	v_mov_b32_e32 v23, v13
	v_mov_b32_e32 v20, v8
	v_mov_b32_e32 v21, v12
	v_pk_mul_f32 v[22:23], v[22:23], v[22:23]
	v_mov_b32_e32 v24, v11
	v_mov_b32_e32 v25, v15
	v_pk_fma_f32 v[20:21], v[20:21], v[20:21], v[22:23]
	v_mov_b32_e32 v22, v10
	v_mov_b32_e32 v23, v14
	v_pk_mul_f32 v[24:25], v[24:25], v[24:25]
	global_store_dwordx4 v[18:19], v[8:11], off nt
	global_store_dwordx4 v[18:19], v[12:15], off offset:16 nt
	v_pk_fma_f32 v[22:23], v[22:23], v[22:23], v[24:25]
	v_cvt_pk_bf16_f32 v8, v8, v9
	v_cvt_pk_bf16_f32 v9, v10, v11
	v_cvt_pk_bf16_f32 v10, v12, v13
	v_cvt_pk_bf16_f32 v11, v14, v15
	global_store_dwordx4 v[16:17], v[8:11], off
	v_pk_add_f32 v[20:21], v[20:21], v[22:23]
	s_nop 0
	v_add_f32_e32 v20, v20, v21
.LBB0_595:
	s_or_b64 exec, exec, s[0:1]
	s_and_saveexec_b64 s[0:1], vcc
	s_cbranch_execz .LBB0_597
	s_waitcnt vmcnt(1)
	v_pk_fma_f32 v[0:1], v[0:1], 0.5, v[68:69] op_sel_hi:[1,0,1]
	s_waitcnt vmcnt(0)
	v_pk_fma_f32 v[4:5], v[4:5], 0.5, v[64:65] op_sel_hi:[1,0,1]
	v_pk_fma_f32 v[2:3], v[2:3], 0.5, v[70:71] op_sel_hi:[1,0,1]
	v_pk_fma_f32 v[6:7], v[6:7], 0.5, v[66:67] op_sel_hi:[1,0,1]
	v_mov_b32_e32 v10, v5
	v_mov_b32_e32 v11, v1
	v_mov_b32_e32 v8, v4
	v_mov_b32_e32 v9, v0
	v_pk_mul_f32 v[10:11], v[10:11], v[10:11]
	v_mov_b32_e32 v12, v7
	v_mov_b32_e32 v13, v3
	v_pk_fma_f32 v[8:9], v[8:9], v[8:9], v[10:11]
	v_mov_b32_e32 v10, v6
	v_mov_b32_e32 v11, v2
	v_pk_mul_f32 v[12:13], v[12:13], v[12:13]
	global_store_dwordx4 v[18:19], v[4:7], off offset:128 nt
	global_store_dwordx4 v[18:19], v[0:3], off offset:144 nt
	v_pk_fma_f32 v[10:11], v[10:11], v[10:11], v[12:13]
	v_cvt_pk_bf16_f32 v4, v4, v5
	v_cvt_pk_bf16_f32 v5, v6, v7
	v_cvt_pk_bf16_f32 v6, v0, v1
	v_cvt_pk_bf16_f32 v7, v2, v3
	global_store_dwordx4 v[16:17], v[4:7], off offset:64
	v_pk_add_f32 v[8:9], v[8:9], v[10:11]
	s_nop 0
	v_add_f32_e32 v8, v8, v9
	v_add_f32_e32 v20, v8, v20

; __device__ __forceinline__ unsigned cvt_pk_bf16(float lo, float hi) { unsigned r; asm volatile("v_cvt_pk_bf16_f32 %0, %1, %2" : "=v"(r) : "v"(lo), "v"(hi)); return r; }
; #define SCHED_BAR() __builtin_amdgcn_sched_barrier(0)
;     __device__ __forceinline__ void operator()(const Acc& acc, const Unit& u, int wr, int wc, int fr, int fq) const {
;     ...
;             for (int m = 0; m < 4; ++m) {
;                 const int row = u.pm * 256 + ai * 128 + wr * 64 + m * 16 + fr; const int rr = row < MREAL ? row : 0;
;                 const float* res = ((MODE == 0) ? xin_row(P, rr) : (const float*)x1_row(P, rr)) + colb;
; #pragma unroll
;                 for (int bj = 0; bj < 2; ++bj)
; #pragma unroll
;                     for (int n = 0; n < 2; ++n) R[m][bj][n] = *(const f32x4*)(res + bj * 32 + n * 4);
;             }
;             SCHED_BAR();
; #pragma unroll
;             for (int m = 0; m < 4; ++m) {
;                 const int row = u.pm * 256 + ai * 128 + wr * 64 + m * 16 + fr;
;                 const bool ok = row < MREAL; const int rr = ok ? row : 0;
;                 float* dst = ((MODE == 2) ? y_row(P, rr) : x1_row(P, rr)) + colb;
;                 float part = 0.f;
; #pragma unroll
;                 for (int bj = 0; bj < 2; ++bj) {
;                     const f32x4 o0 = R[m][bj][0] + acc[ai][bj][m][0] * sc, o1 = R[m][bj][1] + acc[ai][bj][m][1] * sc;
;                     if (ok) {
;                         *(f32x4*)(dst + bj * 32) = o0; *(f32x4*)(dst + bj * 32 + 4) = o1;
;                         if (MODE != 2) { part += ((o0[0] * o0[0] + o0[1] * o0[1]) + (o0[2] * o0[2] + o0[3] * o0[3])) + ((o1[0] * o1[0] + o1[1] * o1[1]) + (o1[2] * o1[2] + o1[3] * o1[3]));
;                             u32x4 w; w.x = cvt_pk_bf16(o0[0], o0[1]); w.y = cvt_pk_bf16(o0[2], o0[3]); w.z = cvt_pk_bf16(o1[0], o1[1]); w.w = cvt_pk_bf16(o1[2], o1[3]);
;                             *(u32x4*)(xb + (size_t)row * DM + colb + bj * 32) = w; }
.LBB0_1601:
	v_lshl_add_u32 v206, s0, 8, v209
	v_cmp_gt_i32_e64 s[14:15], s50, v206
	v_readlane_b32 s52, v254, 1
	v_readlane_b32 s58, v254, 7
	v_cndmask_b32_e64 v128, 0, v206, s[14:15]
	v_readlane_b32 s59, v254, 8
	v_add_u32_e32 v130, 0xffff8000, v128
	v_ashrrev_i32_e32 v129, 31, v128
	v_cmp_gt_i32_e32 vcc, s42, v128
	s_mov_b64 s[10:11], s[58:59]
	v_lshl_or_b32 v204, s2, 8, v229
	v_cndmask_b32_e32 v129, 0, v129, vcc
	v_cndmask_b32_e32 v128, v130, v128, vcc
	v_mov_b32_e32 v132, s47
	v_mov_b32_e32 v133, s11
	v_mov_b32_e32 v134, s46
	v_mov_b32_e32 v135, s10
	v_ashrrev_i32_e32 v205, 31, v204
	v_cndmask_b32_e32 v131, v132, v133, vcc
	v_cndmask_b32_e32 v130, v134, v135, vcc
	v_lshlrev_b64 v[128:129], 12, v[128:129]
	v_or_b32_e32 v220, 16, v206
	v_lshl_add_u64 v[128:129], v[130:131], 0, v[128:129]
	v_lshlrev_b64 v[210:211], 2, v[204:205]
	v_cmp_gt_i32_e64 s[12:13], s50, v220
	v_lshl_add_u64 v[224:225], v[128:129], 0, v[210:211]
	v_or_b32_e32 v216, 32, v206
	v_cndmask_b32_e64 v128, 0, v220, s[12:13]
	v_add_u32_e32 v130, 0xffff8000, v128
	v_ashrrev_i32_e32 v129, 31, v128
	v_cmp_gt_i32_e32 vcc, s42, v128
	v_cmp_gt_i32_e64 s[10:11], s50, v216
	v_or_b32_e32 v212, 48, v206
	v_cndmask_b32_e32 v129, 0, v129, vcc
	v_cndmask_b32_e32 v128, v130, v128, vcc
	v_cndmask_b32_e32 v131, v132, v133, vcc
	v_cndmask_b32_e32 v130, v134, v135, vcc
	v_lshlrev_b64 v[128:129], 12, v[128:129]
	v_lshl_add_u64 v[128:129], v[130:131], 0, v[128:129]
	v_lshl_add_u64 v[222:223], v[128:129], 0, v[210:211]
	v_cndmask_b32_e64 v128, 0, v216, s[10:11]
	v_add_u32_e32 v130, 0xffff8000, v128
	v_ashrrev_i32_e32 v129, 31, v128
	v_cmp_gt_i32_e32 vcc, s42, v128
	global_load_dwordx4 v[188:191], v[224:225], off offset:16 nt
	global_load_dwordx4 v[184:187], v[224:225], off nt
	global_load_dwordx4 v[180:183], v[224:225], off offset:144 nt
	global_load_dwordx4 v[176:179], v[224:225], off offset:128 nt
	v_cndmask_b32_e32 v129, 0, v129, vcc
	v_cndmask_b32_e32 v128, v130, v128, vcc
	v_cndmask_b32_e32 v131, v132, v133, vcc
	v_cndmask_b32_e32 v130, v134, v135, vcc
	v_lshlrev_b64 v[128:129], 12, v[128:129]
	v_lshl_add_u64 v[128:129], v[130:131], 0, v[128:129]
	v_cmp_gt_i32_e32 vcc, s50, v212
	v_lshl_add_u64 v[218:219], v[128:129], 0, v[210:211]
	global_load_dwordx4 v[172:175], v[222:223], off offset:16 nt
	global_load_dwordx4 v[168:171], v[222:223], off nt
	global_load_dwordx4 v[164:167], v[222:223], off offset:144 nt
	global_load_dwordx4 v[160:163], v[222:223], off offset:128 nt
	v_cndmask_b32_e32 v128, 0, v212, vcc
	v_add_u32_e32 v130, 0xffff8000, v128
	v_ashrrev_i32_e32 v129, 31, v128
	v_cmp_gt_i32_e64 s[0:1], s42, v128
	global_load_dwordx4 v[156:159], v[218:219], off offset:16 nt
	global_load_dwordx4 v[152:155], v[218:219], off nt
	global_load_dwordx4 v[148:151], v[218:219], off offset:144 nt
	global_load_dwordx4 v[144:147], v[218:219], off offset:128 nt
	v_cndmask_b32_e64 v129, 0, v129, s[0:1]
	v_cndmask_b32_e64 v128, v130, v128, s[0:1]
	v_cndmask_b32_e64 v131, v132, v133, s[0:1]
	v_cndmask_b32_e64 v130, v134, v135, s[0:1]
	v_lshlrev_b64 v[128:129], 12, v[128:129]
	v_lshl_add_u64 v[128:129], v[130:131], 0, v[128:129]
	v_lshl_add_u64 v[214:215], v[128:129], 0, v[210:211]
	global_load_dwordx4 v[140:143], v[214:215], off offset:16 nt
	global_load_dwordx4 v[136:139], v[214:215], off nt
	global_load_dwordx4 v[132:135], v[214:215], off offset:144 nt
	global_load_dwordx4 v[128:131], v[214:215], off offset:128 nt
	v_readlane_b32 s53, v254, 2
	v_readlane_b32 s54, v254, 3
	v_readlane_b32 s55, v254, 4
	v_readlane_b32 s56, v254, 5
	v_readlane_b32 s57, v254, 6
	v_ashrrev_i32_e32 v207, 31, v206
	v_lshlrev_b64 v[226:227], 11, v[206:207]
	v_lshl_add_u64 v[226:227], s[18:19], 0, v[226:227]
	v_mov_b32_e32 v213, 0
	v_lshl_add_u64 v[226:227], v[204:205], 1, v[226:227]
	s_and_saveexec_b64 s[0:1], s[14:15]
	s_cbranch_execz .LBB0_1603
	s_waitcnt vmcnt(0)
	v_pk_add_f32 v[124:125], v[124:125], v[188:189]
	v_pk_add_f32 v[120:121], v[120:121], v[184:185]
	v_pk_add_f32 v[126:127], v[126:127], v[190:191]
	v_pk_add_f32 v[122:123], v[122:123], v[186:187]
	v_mov_b32_e32 v186, v121
	v_mov_b32_e32 v187, v125
	v_mov_b32_e32 v184, v120
	v_mov_b32_e32 v185, v124
	v_pk_mul_f32 v[186:187], v[186:187], v[186:187]
	v_mov_b32_e32 v188, v123
	v_mov_b32_e32 v189, v127
	v_pk_fma_f32 v[184:185], v[184:185], v[184:185], v[186:187]
	v_mov_b32_e32 v186, v122
	v_mov_b32_e32 v187, v126
	v_pk_mul_f32 v[188:189], v[188:189], v[188:189]
	global_store_dwordx4 v[224:225], v[120:123], off nt
	global_store_dwordx4 v[224:225], v[124:127], off offset:16 nt
	v_pk_fma_f32 v[186:187], v[186:187], v[186:187], v[188:189]
	v_cvt_pk_bf16_f32 v120, v120, v121
	v_cvt_pk_bf16_f32 v121, v122, v123
	v_cvt_pk_bf16_f32 v122, v124, v125
	v_cvt_pk_bf16_f32 v123, v126, v127
	global_store_dwordx4 v[226:227], v[120:123], off
	v_pk_add_f32 v[184:185], v[184:185], v[186:187]
	s_nop 0
	v_add_f32_e32 v213, v184, v185
.LBB0_1603:
	s_or_b64 exec, exec, s[0:1]
	s_and_saveexec_b64 s[0:1], s[14:15]
	s_cbranch_execz .LBB0_1605
	s_waitcnt vmcnt(0)
	v_pk_add_f32 v[116:117], v[116:117], v[180:181]
	v_pk_add_f32 v[112:113], v[112:113], v[176:177]
	v_pk_add_f32 v[118:119], v[118:119], v[182:183]
	v_pk_add_f32 v[114:115], v[114:115], v[178:179]
	v_mov_b32_e32 v122, v113
	v_mov_b32_e32 v123, v117
	v_mov_b32_e32 v120, v112
	v_mov_b32_e32 v121, v116
	v_pk_mul_f32 v[122:123], v[122:123], v[122:123]
	v_mov_b32_e32 v124, v115
	v_mov_b32_e32 v125, v119
	v_pk_fma_f32 v[120:121], v[120:121], v[120:121], v[122:123]
	v_mov_b32_e32 v122, v114
	v_mov_b32_e32 v123, v118
	v_pk_mul_f32 v[124:125], v[124:125], v[124:125]
	global_store_dwordx4 v[224:225], v[112:115], off offset:128 nt
	global_store_dwordx4 v[224:225], v[116:119], off offset:144 nt
	v_pk_fma_f32 v[122:123], v[122:123], v[122:123], v[124:125]
	v_cvt_pk_bf16_f32 v112, v112, v113
	v_cvt_pk_bf16_f32 v113, v114, v115
	v_cvt_pk_bf16_f32 v114, v116, v117
	v_cvt_pk_bf16_f32 v115, v118, v119
	global_store_dwordx4 v[226:227], v[112:115], off offset:64
	v_pk_add_f32 v[120:121], v[120:121], v[122:123]
	s_nop 0
	v_add_f32_e32 v120, v120, v121
	v_add_f32_e32 v213, v120, v213

; __device__ __forceinline__ unsigned cvt_pk_bf16(float lo, float hi) { unsigned r; asm volatile("v_cvt_pk_bf16_f32 %0, %1, %2" : "=v"(r) : "v"(lo), "v"(hi)); return r; }
;     __device__ __forceinline__ void operator()(const Acc& acc, const Unit& u, int wr, int wc, int fr, int fq) const {
;     ...
;             for (int m = 0; m < 4; ++m) {
;                 const int row = u.pm * 256 + ai * 128 + wr * 64 + m * 16 + fr;
;                 const bool ok = row < MREAL; const int rr = ok ? row : 0;
;                 float* dst = ((MODE == 2) ? y_row(P, rr) : x1_row(P, rr)) + colb;
;                 float part = 0.f;
; #pragma unroll
;                 for (int bj = 0; bj < 2; ++bj) {
;                     const f32x4 o0 = R[m][bj][0] + acc[ai][bj][m][0] * sc, o1 = R[m][bj][1] + acc[ai][bj][m][1] * sc;
;                     if (ok) {
;                         *(f32x4*)(dst + bj * 32) = o0; *(f32x4*)(dst + bj * 32 + 4) = o1;
;                         if (MODE != 2) { part += ((o0[0] * o0[0] + o0[1] * o0[1]) + (o0[2] * o0[2] + o0[3] * o0[3])) + ((o1[0] * o1[0] + o1[1] * o1[1]) + (o1[2] * o1[2] + o1[3] * o1[3]));
;                             u32x4 w; w.x = cvt_pk_bf16(o0[0], o0[1]); w.y = cvt_pk_bf16(o0[2], o0[3]); w.z = cvt_pk_bf16(o1[0], o1[1]); w.w = cvt_pk_bf16(o1[2], o1[3]);
;                             *(u32x4*)(xb + (size_t)row * DM + colb + bj * 32) = w; }
.LBB0_1607:
	s_or_b64 exec, exec, s[0:1]
	v_ashrrev_i32_e32 v221, 31, v220
	s_waitcnt lgkmcnt(0)
	v_lshlrev_b64 v[112:113], 11, v[220:221]
	v_lshl_add_u64 v[112:113], s[18:19], 0, v[112:113]
	v_mov_b32_e32 v114, 0
	v_lshl_add_u64 v[112:113], v[204:205], 1, v[112:113]
	s_and_saveexec_b64 s[0:1], s[12:13]
	s_cbranch_execz .LBB0_1609
	v_pk_add_f32 v[108:109], v[108:109], v[172:173]
	v_pk_add_f32 v[104:105], v[104:105], v[168:169]
	v_pk_add_f32 v[110:111], v[110:111], v[174:175]
	v_pk_add_f32 v[106:107], v[106:107], v[170:171]
	v_mov_b32_e32 v116, v105
	v_mov_b32_e32 v117, v109
	v_mov_b32_e32 v114, v104
	v_mov_b32_e32 v115, v108
	v_pk_mul_f32 v[116:117], v[116:117], v[116:117]
	v_mov_b32_e32 v118, v107
	v_mov_b32_e32 v119, v111
	v_pk_fma_f32 v[114:115], v[114:115], v[114:115], v[116:117]
	v_mov_b32_e32 v116, v106
	v_mov_b32_e32 v117, v110
	v_pk_mul_f32 v[118:119], v[118:119], v[118:119]
	global_store_dwordx4 v[222:223], v[104:107], off nt
	global_store_dwordx4 v[222:223], v[108:111], off offset:16 nt
	v_pk_fma_f32 v[116:117], v[116:117], v[116:117], v[118:119]
	v_cvt_pk_bf16_f32 v104, v104, v105
	v_cvt_pk_bf16_f32 v105, v106, v107
	v_cvt_pk_bf16_f32 v106, v108, v109
	v_cvt_pk_bf16_f32 v107, v110, v111
	global_store_dwordx4 v[112:113], v[104:107], off
	v_pk_add_f32 v[114:115], v[114:115], v[116:117]
	s_nop 0
	v_add_f32_e32 v114, v114, v115
.LBB0_1609:
	s_or_b64 exec, exec, s[0:1]
	s_and_saveexec_b64 s[0:1], s[12:13]
	s_cbranch_execz .LBB0_1611
	v_pk_add_f32 v[100:101], v[100:101], v[164:165]
	v_pk_add_f32 v[96:97], v[96:97], v[160:161]
	v_pk_add_f32 v[102:103], v[102:103], v[166:167]
	v_pk_add_f32 v[98:99], v[98:99], v[162:163]
	v_mov_b32_e32 v106, v97
	v_mov_b32_e32 v107, v101
	v_mov_b32_e32 v104, v96
	v_mov_b32_e32 v105, v100
	v_pk_mul_f32 v[106:107], v[106:107], v[106:107]
	v_mov_b32_e32 v108, v99
	v_mov_b32_e32 v109, v103
	v_pk_fma_f32 v[104:105], v[104:105], v[104:105], v[106:107]
	v_mov_b32_e32 v106, v98
	v_mov_b32_e32 v107, v102
	v_pk_mul_f32 v[108:109], v[108:109], v[108:109]
	global_store_dwordx4 v[222:223], v[96:99], off offset:128 nt
	global_store_dwordx4 v[222:223], v[100:103], off offset:144 nt
	v_pk_fma_f32 v[106:107], v[106:107], v[106:107], v[108:109]
	v_cvt_pk_bf16_f32 v96, v96, v97
	v_cvt_pk_bf16_f32 v97, v98, v99
	v_cvt_pk_bf16_f32 v98, v100, v101
	v_cvt_pk_bf16_f32 v99, v102, v103
	global_store_dwordx4 v[112:113], v[96:99], off offset:64
	v_pk_add_f32 v[104:105], v[104:105], v[106:107]
	s_nop 0
	v_add_f32_e32 v104, v104, v105
	v_add_f32_e32 v114, v104, v114

; __device__ __forceinline__ unsigned cvt_pk_bf16(float lo, float hi) { unsigned r; asm volatile("v_cvt_pk_bf16_f32 %0, %1, %2" : "=v"(r) : "v"(lo), "v"(hi)); return r; }
;     __device__ __forceinline__ void operator()(const Acc& acc, const Unit& u, int wr, int wc, int fr, int fq) const {
;     ...
;             for (int m = 0; m < 4; ++m) {
;                 const int row = u.pm * 256 + ai * 128 + wr * 64 + m * 16 + fr;
;                 const bool ok = row < MREAL; const int rr = ok ? row : 0;
;                 float* dst = ((MODE == 2) ? y_row(P, rr) : x1_row(P, rr)) + colb;
;                 float part = 0.f;
; #pragma unroll
;                 for (int bj = 0; bj < 2; ++bj) {
;                     const f32x4 o0 = R[m][bj][0] + acc[ai][bj][m][0] * sc, o1 = R[m][bj][1] + acc[ai][bj][m][1] * sc;
;                     if (ok) {
;                         *(f32x4*)(dst + bj * 32) = o0; *(f32x4*)(dst + bj * 32 + 4) = o1;
;                         if (MODE != 2) { part += ((o0[0] * o0[0] + o0[1] * o0[1]) + (o0[2] * o0[2] + o0[3] * o0[3])) + ((o1[0] * o1[0] + o1[1] * o1[1]) + (o1[2] * o1[2] + o1[3] * o1[3]));
;                             u32x4 w; w.x = cvt_pk_bf16(o0[0], o0[1]); w.y = cvt_pk_bf16(o0[2], o0[3]); w.z = cvt_pk_bf16(o1[0], o1[1]); w.w = cvt_pk_bf16(o1[2], o1[3]);
;                             *(u32x4*)(xb + (size_t)row * DM + colb + bj * 32) = w; }
.LBB0_1613:
	s_or_b64 exec, exec, s[0:1]
	v_ashrrev_i32_e32 v217, 31, v216
	s_waitcnt lgkmcnt(0)
	v_lshlrev_b64 v[96:97], 11, v[216:217]
	v_lshl_add_u64 v[96:97], s[18:19], 0, v[96:97]
	v_mov_b32_e32 v98, 0
	v_lshl_add_u64 v[96:97], v[204:205], 1, v[96:97]
	s_and_saveexec_b64 s[0:1], s[10:11]
	s_cbranch_execz .LBB0_1615
	v_pk_add_f32 v[92:93], v[92:93], v[156:157]
	v_pk_add_f32 v[88:89], v[88:89], v[152:153]
	v_pk_add_f32 v[94:95], v[94:95], v[158:159]
	v_pk_add_f32 v[90:91], v[90:91], v[154:155]
	v_mov_b32_e32 v100, v89
	v_mov_b32_e32 v101, v93
	v_mov_b32_e32 v98, v88
	v_mov_b32_e32 v99, v92
	v_pk_mul_f32 v[100:101], v[100:101], v[100:101]
	v_mov_b32_e32 v102, v91
	v_mov_b32_e32 v103, v95
	v_pk_fma_f32 v[98:99], v[98:99], v[98:99], v[100:101]
	v_mov_b32_e32 v100, v90
	v_mov_b32_e32 v101, v94
	v_pk_mul_f32 v[102:103], v[102:103], v[102:103]
	global_store_dwordx4 v[218:219], v[88:91], off nt
	global_store_dwordx4 v[218:219], v[92:95], off offset:16 nt
	v_pk_fma_f32 v[100:101], v[100:101], v[100:101], v[102:103]
	v_cvt_pk_bf16_f32 v88, v88, v89
	v_cvt_pk_bf16_f32 v89, v90, v91
	v_cvt_pk_bf16_f32 v90, v92, v93
	v_cvt_pk_bf16_f32 v91, v94, v95
	global_store_dwordx4 v[96:97], v[88:91], off
	v_pk_add_f32 v[98:99], v[98:99], v[100:101]
	s_nop 0
	v_add_f32_e32 v98, v98, v99
.LBB0_1615:
	s_or_b64 exec, exec, s[0:1]
	s_and_saveexec_b64 s[0:1], s[10:11]
	s_cbranch_execz .LBB0_1617
	v_pk_add_f32 v[84:85], v[84:85], v[148:149]
	v_pk_add_f32 v[80:81], v[80:81], v[144:145]
	v_pk_add_f32 v[86:87], v[86:87], v[150:151]
	v_pk_add_f32 v[82:83], v[82:83], v[146:147]
	v_mov_b32_e32 v90, v81
	v_mov_b32_e32 v91, v85
	v_mov_b32_e32 v88, v80
	v_mov_b32_e32 v89, v84
	v_pk_mul_f32 v[90:91], v[90:91], v[90:91]
	v_mov_b32_e32 v92, v83
	v_mov_b32_e32 v93, v87
	v_pk_fma_f32 v[88:89], v[88:89], v[88:89], v[90:91]
	v_mov_b32_e32 v90, v82
	v_mov_b32_e32 v91, v86
	v_pk_mul_f32 v[92:93], v[92:93], v[92:93]
	global_store_dwordx4 v[218:219], v[80:83], off offset:128 nt
	global_store_dwordx4 v[218:219], v[84:87], off offset:144 nt
	v_pk_fma_f32 v[90:91], v[90:91], v[90:91], v[92:93]
	v_cvt_pk_bf16_f32 v80, v80, v81
	v_cvt_pk_bf16_f32 v81, v82, v83
	v_cvt_pk_bf16_f32 v82, v84, v85
	v_cvt_pk_bf16_f32 v83, v86, v87
	global_store_dwordx4 v[96:97], v[80:83], off offset:64
	v_pk_add_f32 v[88:89], v[88:89], v[90:91]
	s_nop 0
	v_add_f32_e32 v88, v88, v89
	v_add_f32_e32 v98, v88, v98

; __device__ __forceinline__ unsigned cvt_pk_bf16(float lo, float hi) { unsigned r; asm volatile("v_cvt_pk_bf16_f32 %0, %1, %2" : "=v"(r) : "v"(lo), "v"(hi)); return r; }
;     __device__ __forceinline__ void operator()(const Acc& acc, const Unit& u, int wr, int wc, int fr, int fq) const {
;     ...
;             for (int m = 0; m < 4; ++m) {
;                 const int row = u.pm * 256 + ai * 128 + wr * 64 + m * 16 + fr;
;                 const bool ok = row < MREAL; const int rr = ok ? row : 0;
;                 float* dst = ((MODE == 2) ? y_row(P, rr) : x1_row(P, rr)) + colb;
;                 float part = 0.f;
; #pragma unroll
;                 for (int bj = 0; bj < 2; ++bj) {
;                     const f32x4 o0 = R[m][bj][0] + acc[ai][bj][m][0] * sc, o1 = R[m][bj][1] + acc[ai][bj][m][1] * sc;
;                     if (ok) {
;                         *(f32x4*)(dst + bj * 32) = o0; *(f32x4*)(dst + bj * 32 + 4) = o1;
;                         if (MODE != 2) { part += ((o0[0] * o0[0] + o0[1] * o0[1]) + (o0[2] * o0[2] + o0[3] * o0[3])) + ((o1[0] * o1[0] + o1[1] * o1[1]) + (o1[2] * o1[2] + o1[3] * o1[3]));
;                             u32x4 w; w.x = cvt_pk_bf16(o0[0], o0[1]); w.y = cvt_pk_bf16(o0[2], o0[3]); w.z = cvt_pk_bf16(o1[0], o1[1]); w.w = cvt_pk_bf16(o1[2], o1[3]);
;                             *(u32x4*)(xb + (size_t)row * DM + colb + bj * 32) = w; }
.LBB0_1619:
	s_or_b64 exec, exec, s[0:1]
	v_ashrrev_i32_e32 v213, 31, v212
	s_waitcnt lgkmcnt(0)
	v_lshlrev_b64 v[80:81], 11, v[212:213]
	v_lshl_add_u64 v[80:81], s[18:19], 0, v[80:81]
	v_mov_b32_e32 v82, 0
	v_lshl_add_u64 v[80:81], v[204:205], 1, v[80:81]
	s_and_saveexec_b64 s[0:1], vcc
	s_cbranch_execz .LBB0_1621
	v_pk_add_f32 v[76:77], v[76:77], v[140:141]
	v_pk_add_f32 v[72:73], v[72:73], v[136:137]
	v_pk_add_f32 v[78:79], v[78:79], v[142:143]
	v_pk_add_f32 v[74:75], v[74:75], v[138:139]
	v_mov_b32_e32 v84, v73
	v_mov_b32_e32 v85, v77
	v_mov_b32_e32 v82, v72
	v_mov_b32_e32 v83, v76
	v_pk_mul_f32 v[84:85], v[84:85], v[84:85]
	v_mov_b32_e32 v86, v75
	v_mov_b32_e32 v87, v79
	v_pk_fma_f32 v[82:83], v[82:83], v[82:83], v[84:85]
	v_mov_b32_e32 v84, v74
	v_mov_b32_e32 v85, v78
	v_pk_mul_f32 v[86:87], v[86:87], v[86:87]
	global_store_dwordx4 v[214:215], v[72:75], off nt
	global_store_dwordx4 v[214:215], v[76:79], off offset:16 nt
	v_pk_fma_f32 v[84:85], v[84:85], v[84:85], v[86:87]
	v_cvt_pk_bf16_f32 v72, v72, v73
	v_cvt_pk_bf16_f32 v73, v74, v75
	v_cvt_pk_bf16_f32 v74, v76, v77
	v_cvt_pk_bf16_f32 v75, v78, v79
	global_store_dwordx4 v[80:81], v[72:75], off
	v_pk_add_f32 v[82:83], v[82:83], v[84:85]
	s_nop 0
	v_add_f32_e32 v82, v82, v83
.LBB0_1621:
	s_or_b64 exec, exec, s[0:1]
	s_and_saveexec_b64 s[0:1], vcc
	s_cbranch_execz .LBB0_1623
	v_pk_add_f32 v[68:69], v[68:69], v[132:133]
	v_pk_add_f32 v[64:65], v[64:65], v[128:129]
	v_pk_add_f32 v[70:71], v[70:71], v[134:135]
	v_pk_add_f32 v[66:67], v[66:67], v[130:131]
	v_mov_b32_e32 v74, v65
	v_mov_b32_e32 v75, v69
	v_mov_b32_e32 v72, v64
	v_mov_b32_e32 v73, v68
	v_pk_mul_f32 v[74:75], v[74:75], v[74:75]
	v_mov_b32_e32 v76, v67
	v_mov_b32_e32 v77, v71
	v_pk_fma_f32 v[72:73], v[72:73], v[72:73], v[74:75]
	v_mov_b32_e32 v74, v66
	v_mov_b32_e32 v75, v70
	v_pk_mul_f32 v[76:77], v[76:77], v[76:77]
	global_store_dwordx4 v[214:215], v[64:67], off offset:128 nt
	global_store_dwordx4 v[214:215], v[68:71], off offset:144 nt
	v_pk_fma_f32 v[74:75], v[74:75], v[74:75], v[76:77]
	v_cvt_pk_bf16_f32 v64, v64, v65
	v_cvt_pk_bf16_f32 v65, v66, v67
	v_cvt_pk_bf16_f32 v66, v68, v69
	v_cvt_pk_bf16_f32 v67, v70, v71
	global_store_dwordx4 v[80:81], v[64:67], off offset:64
	v_pk_add_f32 v[72:73], v[72:73], v[74:75]
	s_nop 0
	v_add_f32_e32 v72, v72, v73
	v_add_f32_e32 v82, v72, v82

; __device__ __forceinline__ unsigned cvt_pk_bf16(float lo, float hi) { unsigned r; asm volatile("v_cvt_pk_bf16_f32 %0, %1, %2" : "=v"(r) : "v"(lo), "v"(hi)); return r; }
; #define SCHED_BAR() __builtin_amdgcn_sched_barrier(0)
;     __device__ __forceinline__ void operator()(const Acc& acc, const Unit& u, int wr, int wc, int fr, int fq) const {
;     ...
;         for (int ai = 0; ai < 2; ++ai) {
;             f32x4 R[4][2][2];
; #pragma unroll
;             for (int m = 0; m < 4; ++m) {
;                 const int row = u.pm * 256 + ai * 128 + wr * 64 + m * 16 + fr; const int rr = row < MREAL ? row : 0;
;                 const float* res = ((MODE == 0) ? xin_row(P, rr) : (const float*)x1_row(P, rr)) + colb;
; #pragma unroll
;                 for (int bj = 0; bj < 2; ++bj)
; #pragma unroll
;                     for (int n = 0; n < 2; ++n) R[m][bj][n] = *(const f32x4*)(res + bj * 32 + n * 4);
;             }
;             SCHED_BAR();
; #pragma unroll
;             for (int m = 0; m < 4; ++m) {
;                 const int row = u.pm * 256 + ai * 128 + wr * 64 + m * 16 + fr;
;                 const bool ok = row < MREAL; const int rr = ok ? row : 0;
;                 float* dst = ((MODE == 2) ? y_row(P, rr) : x1_row(P, rr)) + colb;
;                 float part = 0.f;
; #pragma unroll
;                 for (int bj = 0; bj < 2; ++bj) {
;                     const f32x4 o0 = R[m][bj][0] + acc[ai][bj][m][0] * sc, o1 = R[m][bj][1] + acc[ai][bj][m][1] * sc;
;                     if (ok) {
;                         *(f32x4*)(dst + bj * 32) = o0; *(f32x4*)(dst + bj * 32 + 4) = o1;
;                         if (MODE != 2) { part += ((o0[0] * o0[0] + o0[1] * o0[1]) + (o0[2] * o0[2] + o0[3] * o0[3])) + ((o1[0] * o1[0] + o1[1] * o1[1]) + (o1[2] * o1[2] + o1[3] * o1[3]));
;                             u32x4 w; w.x = cvt_pk_bf16(o0[0], o0[1]); w.y = cvt_pk_bf16(o0[2], o0[3]); w.z = cvt_pk_bf16(o1[0], o1[1]); w.w = cvt_pk_bf16(o1[2], o1[3]);
;                             *(u32x4*)(xb + (size_t)row * DM + colb + bj * 32) = w; }
.LBB0_1625:
	s_or_b64 exec, exec, s[0:1]
	v_add_u32_e32 v140, 0x80, v206
	v_cmp_gt_i32_e64 s[14:15], s50, v140
	v_readlane_b32 s52, v254, 1
	v_readlane_b32 s58, v254, 7
	v_cndmask_b32_e64 v64, 0, v140, s[14:15]
	v_readlane_b32 s59, v254, 8
	v_add_u32_e32 v66, 0xffff8000, v64
	s_waitcnt lgkmcnt(0)
	v_ashrrev_i32_e32 v65, 31, v64
	v_cmp_gt_i32_e32 vcc, s42, v64
	s_mov_b64 s[10:11], s[58:59]
	v_mov_b32_e32 v68, s47
	v_cndmask_b32_e32 v65, 0, v65, vcc
	v_cndmask_b32_e32 v64, v66, v64, vcc
	v_mov_b32_e32 v69, s11
	v_mov_b32_e32 v70, s46
	v_mov_b32_e32 v71, s10
	v_cndmask_b32_e32 v67, v68, v69, vcc
	v_cndmask_b32_e32 v66, v70, v71, vcc
	v_lshlrev_b64 v[64:65], 12, v[64:65]
	v_add_u32_e32 v136, 0x90, v206
	v_lshl_add_u64 v[64:65], v[66:67], 0, v[64:65]
	v_cmp_gt_i32_e64 s[12:13], s50, v136
	v_lshl_add_u64 v[142:143], v[64:65], 0, v[210:211]
	v_add_u32_e32 v132, 0xa0, v206
	v_cndmask_b32_e64 v64, 0, v136, s[12:13]
	v_add_u32_e32 v66, 0xffff8000, v64
	v_ashrrev_i32_e32 v65, 31, v64
	v_cmp_gt_i32_e32 vcc, s42, v64
	v_cmp_gt_i32_e64 s[10:11], s50, v132
	v_add_u32_e32 v128, 0xb0, v206
	v_cndmask_b32_e32 v65, 0, v65, vcc
	v_cndmask_b32_e32 v64, v66, v64, vcc
	v_cndmask_b32_e32 v67, v68, v69, vcc
	v_cndmask_b32_e32 v66, v70, v71, vcc
	v_lshlrev_b64 v[64:65], 12, v[64:65]
	v_lshl_add_u64 v[64:65], v[66:67], 0, v[64:65]
	v_lshl_add_u64 v[138:139], v[64:65], 0, v[210:211]
	v_cndmask_b32_e64 v64, 0, v132, s[10:11]
	v_add_u32_e32 v66, 0xffff8000, v64
	v_ashrrev_i32_e32 v65, 31, v64
	v_cmp_gt_i32_e32 vcc, s42, v64
	global_load_dwordx4 v[124:127], v[142:143], off offset:16 nt
	global_load_dwordx4 v[120:123], v[142:143], off nt
	global_load_dwordx4 v[116:119], v[142:143], off offset:144 nt
	global_load_dwordx4 v[112:115], v[142:143], off offset:128 nt
	v_cndmask_b32_e32 v65, 0, v65, vcc
	v_cndmask_b32_e32 v64, v66, v64, vcc
	v_cndmask_b32_e32 v67, v68, v69, vcc
	v_cndmask_b32_e32 v66, v70, v71, vcc
	v_lshlrev_b64 v[64:65], 12, v[64:65]
	v_lshl_add_u64 v[64:65], v[66:67], 0, v[64:65]
	v_cmp_gt_i32_e32 vcc, s50, v128
	v_lshl_add_u64 v[134:135], v[64:65], 0, v[210:211]
	global_load_dwordx4 v[108:111], v[138:139], off offset:16 nt
	global_load_dwordx4 v[104:107], v[138:139], off nt
	global_load_dwordx4 v[100:103], v[138:139], off offset:144 nt
	global_load_dwordx4 v[96:99], v[138:139], off offset:128 nt
	v_cndmask_b32_e32 v64, 0, v128, vcc
	v_add_u32_e32 v66, 0xffff8000, v64
	v_ashrrev_i32_e32 v65, 31, v64
	v_cmp_gt_i32_e64 s[0:1], s42, v64
	global_load_dwordx4 v[92:95], v[134:135], off offset:16 nt
	global_load_dwordx4 v[88:91], v[134:135], off nt
	global_load_dwordx4 v[84:87], v[134:135], off offset:144 nt
	global_load_dwordx4 v[80:83], v[134:135], off offset:128 nt
	v_cndmask_b32_e64 v65, 0, v65, s[0:1]
	v_cndmask_b32_e64 v64, v66, v64, s[0:1]
	v_cndmask_b32_e64 v67, v68, v69, s[0:1]
	v_cndmask_b32_e64 v66, v70, v71, s[0:1]
	v_lshlrev_b64 v[64:65], 12, v[64:65]
	v_lshl_add_u64 v[64:65], v[66:67], 0, v[64:65]
	v_lshl_add_u64 v[130:131], v[64:65], 0, v[210:211]
	global_load_dwordx4 v[76:79], v[130:131], off offset:16 nt
	global_load_dwordx4 v[72:75], v[130:131], off nt
	global_load_dwordx4 v[68:71], v[130:131], off offset:144 nt
	global_load_dwordx4 v[64:67], v[130:131], off offset:128 nt
	v_readlane_b32 s53, v254, 2
	v_readlane_b32 s54, v254, 3
	v_readlane_b32 s55, v254, 4
	v_readlane_b32 s56, v254, 5
	v_readlane_b32 s57, v254, 6
	v_ashrrev_i32_e32 v141, 31, v140
	v_lshlrev_b64 v[144:145], 11, v[140:141]
	v_lshl_add_u64 v[144:145], s[18:19], 0, v[144:145]
	v_mov_b32_e32 v129, 0
	v_lshl_add_u64 v[144:145], v[204:205], 1, v[144:145]
	s_and_saveexec_b64 s[0:1], s[14:15]
	s_cbranch_execz .LBB0_1627
	s_waitcnt vmcnt(15)
	v_pk_add_f32 v[60:61], v[60:61], v[124:125]
	s_waitcnt vmcnt(14)
	v_pk_add_f32 v[56:57], v[56:57], v[120:121]
	v_pk_add_f32 v[62:63], v[62:63], v[126:127]
	v_pk_add_f32 v[58:59], v[58:59], v[122:123]
	v_mov_b32_e32 v122, v57
	v_mov_b32_e32 v123, v61
	v_mov_b32_e32 v120, v56
	v_mov_b32_e32 v121, v60
	v_pk_mul_f32 v[122:123], v[122:123], v[122:123]
	v_mov_b32_e32 v124, v59
	v_mov_b32_e32 v125, v63
	v_pk_fma_f32 v[120:121], v[120:121], v[120:121], v[122:123]
	v_mov_b32_e32 v122, v58
	v_mov_b32_e32 v123, v62
	v_pk_mul_f32 v[124:125], v[124:125], v[124:125]
	global_store_dwordx4 v[142:143], v[56:59], off nt
	global_store_dwordx4 v[142:143], v[60:63], off offset:16 nt
	v_pk_fma_f32 v[122:123], v[122:123], v[122:123], v[124:125]
	v_cvt_pk_bf16_f32 v56, v56, v57
	v_cvt_pk_bf16_f32 v57, v58, v59
	v_cvt_pk_bf16_f32 v58, v60, v61
	v_cvt_pk_bf16_f32 v59, v62, v63
	global_store_dwordx4 v[144:145], v[56:59], off
	v_pk_add_f32 v[120:121], v[120:121], v[122:123]
	s_nop 0
	v_add_f32_e32 v129, v120, v121
.LBB0_1627:
	s_or_b64 exec, exec, s[0:1]
	s_and_saveexec_b64 s[0:1], s[14:15]
	s_cbranch_execz .LBB0_1629
	s_waitcnt vmcnt(13)
	v_pk_add_f32 v[52:53], v[52:53], v[116:117]
	s_waitcnt vmcnt(12)
	v_pk_add_f32 v[48:49], v[48:49], v[112:113]
	v_pk_add_f32 v[54:55], v[54:55], v[118:119]
	v_pk_add_f32 v[50:51], v[50:51], v[114:115]
	v_mov_b32_e32 v58, v49
	v_mov_b32_e32 v59, v53
	v_mov_b32_e32 v56, v48
	v_mov_b32_e32 v57, v52
	v_pk_mul_f32 v[58:59], v[58:59], v[58:59]
	v_mov_b32_e32 v60, v51
	v_mov_b32_e32 v61, v55
	v_pk_fma_f32 v[56:57], v[56:57], v[56:57], v[58:59]
	v_mov_b32_e32 v58, v50
	v_mov_b32_e32 v59, v54
	v_pk_mul_f32 v[60:61], v[60:61], v[60:61]
	global_store_dwordx4 v[142:143], v[48:51], off offset:128 nt
	global_store_dwordx4 v[142:143], v[52:55], off offset:144 nt
	v_pk_fma_f32 v[58:59], v[58:59], v[58:59], v[60:61]
	v_cvt_pk_bf16_f32 v48, v48, v49
	v_cvt_pk_bf16_f32 v49, v50, v51
	v_cvt_pk_bf16_f32 v50, v52, v53
	v_cvt_pk_bf16_f32 v51, v54, v55
	global_store_dwordx4 v[144:145], v[48:51], off offset:64
	v_pk_add_f32 v[56:57], v[56:57], v[58:59]
	s_nop 0
	v_add_f32_e32 v56, v56, v57
	v_add_f32_e32 v129, v56, v129

; __device__ __forceinline__ unsigned cvt_pk_bf16(float lo, float hi) { unsigned r; asm volatile("v_cvt_pk_bf16_f32 %0, %1, %2" : "=v"(r) : "v"(lo), "v"(hi)); return r; }
;     __device__ __forceinline__ void operator()(const Acc& acc, const Unit& u, int wr, int wc, int fr, int fq) const {
;     ...
;             for (int m = 0; m < 4; ++m) {
;                 const int row = u.pm * 256 + ai * 128 + wr * 64 + m * 16 + fr;
;                 const bool ok = row < MREAL; const int rr = ok ? row : 0;
;                 float* dst = ((MODE == 2) ? y_row(P, rr) : x1_row(P, rr)) + colb;
;                 float part = 0.f;
; #pragma unroll
;                 for (int bj = 0; bj < 2; ++bj) {
;                     const f32x4 o0 = R[m][bj][0] + acc[ai][bj][m][0] * sc, o1 = R[m][bj][1] + acc[ai][bj][m][1] * sc;
;                     if (ok) {
;                         *(f32x4*)(dst + bj * 32) = o0; *(f32x4*)(dst + bj * 32 + 4) = o1;
;                         if (MODE != 2) { part += ((o0[0] * o0[0] + o0[1] * o0[1]) + (o0[2] * o0[2] + o0[3] * o0[3])) + ((o1[0] * o1[0] + o1[1] * o1[1]) + (o1[2] * o1[2] + o1[3] * o1[3]));
;                             u32x4 w; w.x = cvt_pk_bf16(o0[0], o0[1]); w.y = cvt_pk_bf16(o0[2], o0[3]); w.z = cvt_pk_bf16(o1[0], o1[1]); w.w = cvt_pk_bf16(o1[2], o1[3]);
;                             *(u32x4*)(xb + (size_t)row * DM + colb + bj * 32) = w; }
.LBB0_1631:
	s_or_b64 exec, exec, s[0:1]
	v_ashrrev_i32_e32 v137, 31, v136
	s_waitcnt lgkmcnt(0)
	v_lshlrev_b64 v[48:49], 11, v[136:137]
	v_lshl_add_u64 v[48:49], s[18:19], 0, v[48:49]
	v_mov_b32_e32 v50, 0
	v_lshl_add_u64 v[48:49], v[204:205], 1, v[48:49]
	s_and_saveexec_b64 s[0:1], s[12:13]
	s_cbranch_execz .LBB0_1633
	s_waitcnt vmcnt(11)
	v_pk_add_f32 v[44:45], v[44:45], v[108:109]
	s_waitcnt vmcnt(10)
	v_pk_add_f32 v[40:41], v[40:41], v[104:105]
	v_pk_add_f32 v[46:47], v[46:47], v[110:111]
	v_pk_add_f32 v[42:43], v[42:43], v[106:107]
	v_mov_b32_e32 v52, v41
	v_mov_b32_e32 v53, v45
	v_mov_b32_e32 v50, v40
	v_mov_b32_e32 v51, v44
	v_pk_mul_f32 v[52:53], v[52:53], v[52:53]
	v_mov_b32_e32 v54, v43
	v_mov_b32_e32 v55, v47
	v_pk_fma_f32 v[50:51], v[50:51], v[50:51], v[52:53]
	v_mov_b32_e32 v52, v42
	v_mov_b32_e32 v53, v46
	v_pk_mul_f32 v[54:55], v[54:55], v[54:55]
	global_store_dwordx4 v[138:139], v[40:43], off nt
	global_store_dwordx4 v[138:139], v[44:47], off offset:16 nt
	v_pk_fma_f32 v[52:53], v[52:53], v[52:53], v[54:55]
	v_cvt_pk_bf16_f32 v40, v40, v41
	v_cvt_pk_bf16_f32 v41, v42, v43
	v_cvt_pk_bf16_f32 v42, v44, v45
	v_cvt_pk_bf16_f32 v43, v46, v47
	global_store_dwordx4 v[48:49], v[40:43], off
	v_pk_add_f32 v[50:51], v[50:51], v[52:53]
	s_nop 0
	v_add_f32_e32 v50, v50, v51
.LBB0_1633:
	s_or_b64 exec, exec, s[0:1]
	s_and_saveexec_b64 s[0:1], s[12:13]
	s_cbranch_execz .LBB0_1635
	s_waitcnt vmcnt(9)
	v_pk_add_f32 v[36:37], v[36:37], v[100:101]
	s_waitcnt vmcnt(8)
	v_pk_add_f32 v[32:33], v[32:33], v[96:97]
	v_pk_add_f32 v[38:39], v[38:39], v[102:103]
	v_pk_add_f32 v[34:35], v[34:35], v[98:99]
	v_mov_b32_e32 v42, v33
	v_mov_b32_e32 v43, v37
	v_mov_b32_e32 v40, v32
	v_mov_b32_e32 v41, v36
	v_pk_mul_f32 v[42:43], v[42:43], v[42:43]
	v_mov_b32_e32 v44, v35
	v_mov_b32_e32 v45, v39
	v_pk_fma_f32 v[40:41], v[40:41], v[40:41], v[42:43]
	v_mov_b32_e32 v42, v34
	v_mov_b32_e32 v43, v38
	v_pk_mul_f32 v[44:45], v[44:45], v[44:45]
	global_store_dwordx4 v[138:139], v[32:35], off offset:128 nt
	global_store_dwordx4 v[138:139], v[36:39], off offset:144 nt
	v_pk_fma_f32 v[42:43], v[42:43], v[42:43], v[44:45]
	v_cvt_pk_bf16_f32 v32, v32, v33
	v_cvt_pk_bf16_f32 v33, v34, v35
	v_cvt_pk_bf16_f32 v34, v36, v37
	v_cvt_pk_bf16_f32 v35, v38, v39
	global_store_dwordx4 v[48:49], v[32:35], off offset:64
	v_pk_add_f32 v[40:41], v[40:41], v[42:43]
	s_nop 0
	v_add_f32_e32 v40, v40, v41
	v_add_f32_e32 v50, v40, v50

; __device__ __forceinline__ unsigned cvt_pk_bf16(float lo, float hi) { unsigned r; asm volatile("v_cvt_pk_bf16_f32 %0, %1, %2" : "=v"(r) : "v"(lo), "v"(hi)); return r; }
;     __device__ __forceinline__ void operator()(const Acc& acc, const Unit& u, int wr, int wc, int fr, int fq) const {
;     ...
;             for (int m = 0; m < 4; ++m) {
;                 const int row = u.pm * 256 + ai * 128 + wr * 64 + m * 16 + fr;
;                 const bool ok = row < MREAL; const int rr = ok ? row : 0;
;                 float* dst = ((MODE == 2) ? y_row(P, rr) : x1_row(P, rr)) + colb;
;                 float part = 0.f;
; #pragma unroll
;                 for (int bj = 0; bj < 2; ++bj) {
;                     const f32x4 o0 = R[m][bj][0] + acc[ai][bj][m][0] * sc, o1 = R[m][bj][1] + acc[ai][bj][m][1] * sc;
;                     if (ok) {
;                         *(f32x4*)(dst + bj * 32) = o0; *(f32x4*)(dst + bj * 32 + 4) = o1;
;                         if (MODE != 2) { part += ((o0[0] * o0[0] + o0[1] * o0[1]) + (o0[2] * o0[2] + o0[3] * o0[3])) + ((o1[0] * o1[0] + o1[1] * o1[1]) + (o1[2] * o1[2] + o1[3] * o1[3]));
;                             u32x4 w; w.x = cvt_pk_bf16(o0[0], o0[1]); w.y = cvt_pk_bf16(o0[2], o0[3]); w.z = cvt_pk_bf16(o1[0], o1[1]); w.w = cvt_pk_bf16(o1[2], o1[3]);
;                             *(u32x4*)(xb + (size_t)row * DM + colb + bj * 32) = w; }
.LBB0_1637:
	s_or_b64 exec, exec, s[0:1]
	v_ashrrev_i32_e32 v133, 31, v132
	s_waitcnt lgkmcnt(0)
	v_lshlrev_b64 v[32:33], 11, v[132:133]
	v_lshl_add_u64 v[32:33], s[18:19], 0, v[32:33]
	v_mov_b32_e32 v34, 0
	v_lshl_add_u64 v[32:33], v[204:205], 1, v[32:33]
	s_and_saveexec_b64 s[0:1], s[10:11]
	s_cbranch_execz .LBB0_1639
	s_waitcnt vmcnt(7)
	v_pk_add_f32 v[28:29], v[28:29], v[92:93]
	s_waitcnt vmcnt(6)
	v_pk_add_f32 v[24:25], v[24:25], v[88:89]
	v_pk_add_f32 v[30:31], v[30:31], v[94:95]
	v_pk_add_f32 v[26:27], v[26:27], v[90:91]
	v_mov_b32_e32 v36, v25
	v_mov_b32_e32 v37, v29
	v_mov_b32_e32 v34, v24
	v_mov_b32_e32 v35, v28
	v_pk_mul_f32 v[36:37], v[36:37], v[36:37]
	v_mov_b32_e32 v38, v27
	v_mov_b32_e32 v39, v31
	v_pk_fma_f32 v[34:35], v[34:35], v[34:35], v[36:37]
	v_mov_b32_e32 v36, v26
	v_mov_b32_e32 v37, v30
	v_pk_mul_f32 v[38:39], v[38:39], v[38:39]
	global_store_dwordx4 v[134:135], v[24:27], off nt
	global_store_dwordx4 v[134:135], v[28:31], off offset:16 nt
	v_pk_fma_f32 v[36:37], v[36:37], v[36:37], v[38:39]
	v_cvt_pk_bf16_f32 v24, v24, v25
	v_cvt_pk_bf16_f32 v25, v26, v27
	v_cvt_pk_bf16_f32 v26, v28, v29
	v_cvt_pk_bf16_f32 v27, v30, v31
	global_store_dwordx4 v[32:33], v[24:27], off
	v_pk_add_f32 v[34:35], v[34:35], v[36:37]
	s_nop 0
	v_add_f32_e32 v34, v34, v35
.LBB0_1639:
	s_or_b64 exec, exec, s[0:1]
	s_and_saveexec_b64 s[0:1], s[10:11]
	s_cbranch_execz .LBB0_1641
	s_waitcnt vmcnt(5)
	v_pk_add_f32 v[20:21], v[20:21], v[84:85]
	s_waitcnt vmcnt(4)
	v_pk_add_f32 v[16:17], v[16:17], v[80:81]
	v_pk_add_f32 v[22:23], v[22:23], v[86:87]
	v_pk_add_f32 v[18:19], v[18:19], v[82:83]
	v_mov_b32_e32 v26, v17
	v_mov_b32_e32 v27, v21
	v_mov_b32_e32 v24, v16
	v_mov_b32_e32 v25, v20
	v_pk_mul_f32 v[26:27], v[26:27], v[26:27]
	v_mov_b32_e32 v28, v19
	v_mov_b32_e32 v29, v23
	v_pk_fma_f32 v[24:25], v[24:25], v[24:25], v[26:27]
	v_mov_b32_e32 v26, v18
	v_mov_b32_e32 v27, v22
	v_pk_mul_f32 v[28:29], v[28:29], v[28:29]
	global_store_dwordx4 v[134:135], v[16:19], off offset:128 nt
	global_store_dwordx4 v[134:135], v[20:23], off offset:144 nt
	v_pk_fma_f32 v[26:27], v[26:27], v[26:27], v[28:29]
	v_cvt_pk_bf16_f32 v16, v16, v17
	v_cvt_pk_bf16_f32 v17, v18, v19
	v_cvt_pk_bf16_f32 v18, v20, v21
	v_cvt_pk_bf16_f32 v19, v22, v23
	global_store_dwordx4 v[32:33], v[16:19], off offset:64
	v_pk_add_f32 v[24:25], v[24:25], v[26:27]
	s_nop 0
	v_add_f32_e32 v24, v24, v25
	v_add_f32_e32 v34, v24, v34

; __device__ __forceinline__ unsigned cvt_pk_bf16(float lo, float hi) { unsigned r; asm volatile("v_cvt_pk_bf16_f32 %0, %1, %2" : "=v"(r) : "v"(lo), "v"(hi)); return r; }
;     __device__ __forceinline__ void operator()(const Acc& acc, const Unit& u, int wr, int wc, int fr, int fq) const {
;     ...
;             for (int m = 0; m < 4; ++m) {
;                 const int row = u.pm * 256 + ai * 128 + wr * 64 + m * 16 + fr;
;                 const bool ok = row < MREAL; const int rr = ok ? row : 0;
;                 float* dst = ((MODE == 2) ? y_row(P, rr) : x1_row(P, rr)) + colb;
;                 float part = 0.f;
; #pragma unroll
;                 for (int bj = 0; bj < 2; ++bj) {
;                     const f32x4 o0 = R[m][bj][0] + acc[ai][bj][m][0] * sc, o1 = R[m][bj][1] + acc[ai][bj][m][1] * sc;
;                     if (ok) {
;                         *(f32x4*)(dst + bj * 32) = o0; *(f32x4*)(dst + bj * 32 + 4) = o1;
;                         if (MODE != 2) { part += ((o0[0] * o0[0] + o0[1] * o0[1]) + (o0[2] * o0[2] + o0[3] * o0[3])) + ((o1[0] * o1[0] + o1[1] * o1[1]) + (o1[2] * o1[2] + o1[3] * o1[3]));
;                             u32x4 w; w.x = cvt_pk_bf16(o0[0], o0[1]); w.y = cvt_pk_bf16(o0[2], o0[3]); w.z = cvt_pk_bf16(o1[0], o1[1]); w.w = cvt_pk_bf16(o1[2], o1[3]);
;                             *(u32x4*)(xb + (size_t)row * DM + colb + bj * 32) = w; }
.LBB0_1643:
	s_or_b64 exec, exec, s[0:1]
	v_ashrrev_i32_e32 v129, 31, v128
	s_waitcnt lgkmcnt(0)
	v_lshlrev_b64 v[16:17], 11, v[128:129]
	v_lshl_add_u64 v[16:17], s[18:19], 0, v[16:17]
	v_mov_b32_e32 v18, 0
	v_lshl_add_u64 v[16:17], v[204:205], 1, v[16:17]
	s_and_saveexec_b64 s[0:1], vcc
	s_cbranch_execz .LBB0_1645
	s_waitcnt vmcnt(3)
	v_pk_add_f32 v[12:13], v[12:13], v[76:77]
	s_waitcnt vmcnt(2)
	v_pk_add_f32 v[8:9], v[8:9], v[72:73]
	v_pk_add_f32 v[14:15], v[14:15], v[78:79]
	v_pk_add_f32 v[10:11], v[10:11], v[74:75]
	v_mov_b32_e32 v20, v9
	v_mov_b32_e32 v21, v13
	v_mov_b32_e32 v18, v8
	v_mov_b32_e32 v19, v12
	v_pk_mul_f32 v[20:21], v[20:21], v[20:21]
	v_mov_b32_e32 v22, v11
	v_mov_b32_e32 v23, v15
	v_pk_fma_f32 v[18:19], v[18:19], v[18:19], v[20:21]
	v_mov_b32_e32 v20, v10
	v_mov_b32_e32 v21, v14
	v_pk_mul_f32 v[22:23], v[22:23], v[22:23]
	global_store_dwordx4 v[130:131], v[8:11], off nt
	global_store_dwordx4 v[130:131], v[12:15], off offset:16 nt
	v_pk_fma_f32 v[20:21], v[20:21], v[20:21], v[22:23]
	v_cvt_pk_bf16_f32 v8, v8, v9
	v_cvt_pk_bf16_f32 v9, v10, v11
	v_cvt_pk_bf16_f32 v10, v12, v13
	v_cvt_pk_bf16_f32 v11, v14, v15
	global_store_dwordx4 v[16:17], v[8:11], off
	v_pk_add_f32 v[18:19], v[18:19], v[20:21]
	s_nop 0
	v_add_f32_e32 v18, v18, v19
.LBB0_1645:
	s_or_b64 exec, exec, s[0:1]
	s_and_saveexec_b64 s[0:1], vcc
	s_cbranch_execz .LBB0_1647
	s_waitcnt vmcnt(1)
	v_pk_add_f32 v[0:1], v[0:1], v[68:69]
	s_waitcnt vmcnt(0)
	v_pk_add_f32 v[4:5], v[4:5], v[64:65]
	v_pk_add_f32 v[2:3], v[2:3], v[70:71]
	v_pk_add_f32 v[6:7], v[6:7], v[66:67]
	v_mov_b32_e32 v10, v5
	v_mov_b32_e32 v11, v1
	v_mov_b32_e32 v8, v4
	v_mov_b32_e32 v9, v0
	v_pk_mul_f32 v[10:11], v[10:11], v[10:11]
	v_mov_b32_e32 v12, v7
	v_mov_b32_e32 v13, v3
	v_pk_fma_f32 v[8:9], v[8:9], v[8:9], v[10:11]
	v_mov_b32_e32 v10, v6
	v_mov_b32_e32 v11, v2
	v_pk_mul_f32 v[12:13], v[12:13], v[12:13]
	global_store_dwordx4 v[130:131], v[4:7], off offset:128 nt
	global_store_dwordx4 v[130:131], v[0:3], off offset:144 nt
	v_pk_fma_f32 v[10:11], v[10:11], v[10:11], v[12:13]
	v_cvt_pk_bf16_f32 v4, v4, v5
	v_cvt_pk_bf16_f32 v5, v6, v7
	v_cvt_pk_bf16_f32 v6, v0, v1
	v_cvt_pk_bf16_f32 v7, v2, v3
	global_store_dwordx4 v[16:17], v[4:7], off offset:64
	v_pk_add_f32 v[8:9], v[8:9], v[10:11]
	s_nop 0
	v_add_f32_e32 v8, v8, v9
	v_add_f32_e32 v18, v8, v18

;     __device__ __forceinline__ void operator()(const Acc& acc, const Unit& u, int wr, int wc, int fr, int fq) const {
;     ...
;             for (int m = 0; m < 4; ++m) {
;                 const int row = u.pm * 256 + ai * 128 + wr * 64 + m * 16 + fr; const int rr = row < MREAL ? row : 0;
;                 const float* res = ((MODE == 0) ? xin_row(P, rr) : (const float*)x1_row(P, rr)) + colb;
; #pragma unroll
;                 for (int bj = 0; bj < 2; ++bj)
; #pragma unroll
;                     for (int n = 0; n < 2; ++n) R[m][bj][n] = *(const f32x4*)(res + bj * 32 + n * 4);
.LBB0_1831:
	v_lshl_add_u32 v230, s12, 8, v209
	v_cmp_gt_i32_e64 s[16:17], s46, v230
	v_readlane_b32 s52, v254, 1
	v_readlane_b32 s58, v254, 7
	v_cndmask_b32_e64 v128, 0, v230, s[16:17]
	v_readlane_b32 s59, v254, 8
	v_add_u32_e32 v130, 0xffff8000, v128
	v_ashrrev_i32_e32 v129, 31, v128
	v_cmp_gt_i32_e64 s[14:15], s39, v128
	s_mov_b64 s[6:7], s[58:59]
	v_lshl_or_b32 v212, s13, 8, v225
	v_cndmask_b32_e64 v129, 0, v129, s[14:15]
	v_cndmask_b32_e64 v128, v130, v128, s[14:15]
	v_mov_b32_e32 v132, s43
	v_mov_b32_e32 v133, s7
	v_mov_b32_e32 v134, s42
	v_mov_b32_e32 v135, s6
	v_ashrrev_i32_e32 v213, 31, v212
	v_cndmask_b32_e64 v131, v132, v133, s[14:15]
	v_cndmask_b32_e64 v130, v134, v135, s[14:15]
	v_lshlrev_b64 v[222:223], 12, v[128:129]
	v_lshl_add_u64 v[128:129], v[130:131], 0, v[222:223]
	v_lshlrev_b64 v[214:215], 2, v[212:213]
	v_lshl_add_u64 v[128:129], v[128:129], 0, v[214:215]
	global_load_dwordx4 v[188:191], v[128:129], off offset:16 nt
	global_load_dwordx4 v[184:187], v[128:129], off nt
	global_load_dwordx4 v[180:183], v[128:129], off offset:144 nt
	global_load_dwordx4 v[176:179], v[128:129], off offset:128 nt
	v_or_b32_e32 v128, 16, v230
	v_cmp_gt_i32_e64 s[12:13], s46, v128
	v_readlane_b32 s53, v254, 2
	v_readlane_b32 s54, v254, 3
	v_cndmask_b32_e64 v128, 0, v128, s[12:13]
	v_add_u32_e32 v130, 0xffff8000, v128
	v_ashrrev_i32_e32 v129, 31, v128
	v_cmp_gt_i32_e64 s[10:11], s39, v128
	v_readlane_b32 s55, v254, 4
	v_readlane_b32 s56, v254, 5
	v_cndmask_b32_e64 v129, 0, v129, s[10:11]
	v_cndmask_b32_e64 v128, v130, v128, s[10:11]
	v_cndmask_b32_e64 v131, v132, v133, s[10:11]
	v_cndmask_b32_e64 v130, v134, v135, s[10:11]
	v_lshlrev_b64 v[220:221], 12, v[128:129]
	v_lshl_add_u64 v[128:129], v[130:131], 0, v[220:221]
	v_lshl_add_u64 v[128:129], v[128:129], 0, v[214:215]
	global_load_dwordx4 v[172:175], v[128:129], off offset:16 nt
	global_load_dwordx4 v[168:171], v[128:129], off nt
	global_load_dwordx4 v[164:167], v[128:129], off offset:144 nt
	global_load_dwordx4 v[160:163], v[128:129], off offset:128 nt
	v_or_b32_e32 v128, 32, v230
	v_cmp_gt_i32_e64 s[8:9], s46, v128
	v_readlane_b32 s57, v254, 6
	s_nop 0
	v_cndmask_b32_e64 v128, 0, v128, s[8:9]
	v_add_u32_e32 v130, 0xffff8000, v128
	v_ashrrev_i32_e32 v129, 31, v128
	v_cmp_gt_i32_e64 s[6:7], s39, v128
	s_nop 1
	v_cndmask_b32_e64 v129, 0, v129, s[6:7]
	v_cndmask_b32_e64 v128, v130, v128, s[6:7]
	v_cndmask_b32_e64 v131, v132, v133, s[6:7]
	v_cndmask_b32_e64 v130, v134, v135, s[6:7]
	v_lshlrev_b64 v[218:219], 12, v[128:129]
	v_lshl_add_u64 v[128:129], v[130:131], 0, v[218:219]
	v_lshl_add_u64 v[128:129], v[128:129], 0, v[214:215]
	global_load_dwordx4 v[156:159], v[128:129], off offset:16 nt
	global_load_dwordx4 v[152:155], v[128:129], off nt
	global_load_dwordx4 v[148:151], v[128:129], off offset:144 nt
	global_load_dwordx4 v[144:147], v[128:129], off offset:128 nt
	v_or_b32_e32 v128, 48, v230
	v_cmp_gt_i32_e64 s[2:3], s46, v128
	s_nop 1
	v_cndmask_b32_e64 v128, 0, v128, s[2:3]
	v_add_u32_e32 v130, 0xffff8000, v128
	v_ashrrev_i32_e32 v129, 31, v128
	v_cmp_gt_i32_e32 vcc, s39, v128
	s_nop 1
	v_cndmask_b32_e32 v129, 0, v129, vcc
	v_cndmask_b32_e32 v128, v130, v128, vcc
	v_cndmask_b32_e32 v131, v132, v133, vcc
	v_cndmask_b32_e32 v130, v134, v135, vcc
	v_lshlrev_b64 v[216:217], 12, v[128:129]
	v_lshl_add_u64 v[128:129], v[130:131], 0, v[216:217]
	v_lshl_add_u64 v[128:129], v[128:129], 0, v[214:215]
	global_load_dwordx4 v[140:143], v[128:129], off offset:16 nt
	global_load_dwordx4 v[136:139], v[128:129], off nt
	global_load_dwordx4 v[132:135], v[128:129], off offset:144 nt
	s_nop 0
	global_load_dwordx4 v[128:131], v[128:129], off offset:128 nt
	s_and_saveexec_b64 s[28:29], s[16:17]
	s_cbranch_execnz .LBB0_1841
	s_or_b64 exec, exec, s[28:29]
	s_and_saveexec_b64 s[14:15], s[12:13]
	s_cbranch_execnz .LBB0_1842

; #define SCHED_BAR() __builtin_amdgcn_sched_barrier(0)
;     __device__ __forceinline__ void operator()(const Acc& acc, const Unit& u, int wr, int wc, int fr, int fq) const {
;     ...
;         for (int ai = 0; ai < 2; ++ai) {
;             f32x4 R[4][2][2];
; #pragma unroll
;             for (int m = 0; m < 4; ++m) {
;                 const int row = u.pm * 256 + ai * 128 + wr * 64 + m * 16 + fr; const int rr = row < MREAL ? row : 0;
;                 const float* res = ((MODE == 0) ? xin_row(P, rr) : (const float*)x1_row(P, rr)) + colb;
; #pragma unroll
;                 for (int bj = 0; bj < 2; ++bj)
; #pragma unroll
;                     for (int n = 0; n < 2; ++n) R[m][bj][n] = *(const f32x4*)(res + bj * 32 + n * 4);
;             }
;             SCHED_BAR();
; #pragma unroll
;             for (int m = 0; m < 4; ++m) {
;                 const int row = u.pm * 256 + ai * 128 + wr * 64 + m * 16 + fr;
;                 const bool ok = row < MREAL; const int rr = ok ? row : 0;
;                 float* dst = ((MODE == 2) ? y_row(P, rr) : x1_row(P, rr)) + colb;
;                 float part = 0.f;
; #pragma unroll
;                 for (int bj = 0; bj < 2; ++bj) {
;                     const f32x4 o0 = R[m][bj][0] + acc[ai][bj][m][0] * sc, o1 = R[m][bj][1] + acc[ai][bj][m][1] * sc;
;                     if (ok) {
;                         *(f32x4*)(dst + bj * 32) = o0; *(f32x4*)(dst + bj * 32 + 4) = o1;
.LBB0_1835:
	v_readlane_b32 s8, v254, 1
	v_cndmask_b32_e64 v200, v229, 0, vcc
	v_readlane_b32 s14, v254, 7
	v_readlane_b32 s15, v254, 8
	s_waitcnt vmcnt(0)
	v_pk_fma_f32 v[74:75], v[74:75], 0.5, v[138:139] op_sel_hi:[1,0,1]
	v_pk_fma_f32 v[72:73], v[72:73], 0.5, v[136:137] op_sel_hi:[1,0,1]
	v_lshl_add_u64 v[80:81], s[14:15], 0, v[200:201]
	v_lshl_add_u64 v[80:81], v[80:81], 0, v[216:217]
	v_lshl_add_u64 v[80:81], v[212:213], 2, v[80:81]
	v_pk_fma_f32 v[66:67], v[66:67], 0.5, v[130:131] op_sel_hi:[1,0,1]
	v_pk_fma_f32 v[64:65], v[64:65], 0.5, v[128:129] op_sel_hi:[1,0,1]
	v_readlane_b32 s9, v254, 2
	v_readlane_b32 s10, v254, 3
	v_readlane_b32 s11, v254, 4
	v_readlane_b32 s12, v254, 5
	v_readlane_b32 s13, v254, 6
	v_pk_fma_f32 v[78:79], v[78:79], 0.5, v[142:143] op_sel_hi:[1,0,1]
	v_pk_fma_f32 v[76:77], v[76:77], 0.5, v[140:141] op_sel_hi:[1,0,1]
	global_store_dwordx4 v[80:81], v[72:75], off nt
	global_store_dwordx4 v[80:81], v[76:79], off offset:16 nt
	v_pk_fma_f32 v[70:71], v[70:71], 0.5, v[134:135] op_sel_hi:[1,0,1]
	v_pk_fma_f32 v[68:69], v[68:69], 0.5, v[132:133] op_sel_hi:[1,0,1]
	global_store_dwordx4 v[80:81], v[64:67], off offset:128 nt
	global_store_dwordx4 v[80:81], v[68:71], off offset:144 nt
.LBB0_1836:
	s_or_b64 exec, exec, s[6:7]
	v_add_u32_e32 v64, 0x80, v230
	v_cmp_gt_i32_e64 s[16:17], s46, v64
	v_readlane_b32 s52, v254, 1
	v_readlane_b32 s58, v254, 7
	v_cndmask_b32_e64 v64, 0, v64, s[16:17]
	v_readlane_b32 s59, v254, 8
	v_add_u32_e32 v66, 0xffff8000, v64
	v_ashrrev_i32_e32 v65, 31, v64
	v_cmp_gt_i32_e64 s[14:15], s39, v64
	s_mov_b64 s[6:7], s[58:59]
	v_mov_b32_e32 v68, s43
	v_cndmask_b32_e64 v65, 0, v65, s[14:15]
	v_cndmask_b32_e64 v64, v66, v64, s[14:15]
	v_mov_b32_e32 v69, s7
	v_mov_b32_e32 v70, s42
	v_mov_b32_e32 v71, s6
	v_cndmask_b32_e64 v67, v68, v69, s[14:15]
	v_cndmask_b32_e64 v66, v70, v71, s[14:15]
	s_waitcnt vmcnt(0)
	v_lshlrev_b64 v[134:135], 12, v[64:65]
	v_lshl_add_u64 v[64:65], v[66:67], 0, v[134:135]
	v_lshl_add_u64 v[64:65], v[64:65], 0, v[214:215]
	global_load_dwordx4 v[124:127], v[64:65], off offset:16 nt
	global_load_dwordx4 v[120:123], v[64:65], off nt
	global_load_dwordx4 v[116:119], v[64:65], off offset:144 nt
	global_load_dwordx4 v[112:115], v[64:65], off offset:128 nt
	v_add_u32_e32 v64, 0x90, v230
	v_cmp_gt_i32_e64 s[12:13], s46, v64
	v_readlane_b32 s53, v254, 2
	v_readlane_b32 s54, v254, 3
	v_cndmask_b32_e64 v64, 0, v64, s[12:13]
	v_add_u32_e32 v66, 0xffff8000, v64
	v_ashrrev_i32_e32 v65, 31, v64
	v_cmp_gt_i32_e64 s[10:11], s39, v64
	v_readlane_b32 s55, v254, 4
	v_readlane_b32 s56, v254, 5
	v_cndmask_b32_e64 v65, 0, v65, s[10:11]
	v_cndmask_b32_e64 v64, v66, v64, s[10:11]
	v_cndmask_b32_e64 v67, v68, v69, s[10:11]
	v_cndmask_b32_e64 v66, v70, v71, s[10:11]
	v_lshlrev_b64 v[132:133], 12, v[64:65]
	v_lshl_add_u64 v[64:65], v[66:67], 0, v[132:133]
	v_lshl_add_u64 v[64:65], v[64:65], 0, v[214:215]
	global_load_dwordx4 v[108:111], v[64:65], off offset:16 nt
	global_load_dwordx4 v[104:107], v[64:65], off nt
	global_load_dwordx4 v[100:103], v[64:65], off offset:144 nt
	global_load_dwordx4 v[96:99], v[64:65], off offset:128 nt
	v_add_u32_e32 v64, 0xa0, v230
	v_cmp_gt_i32_e64 s[8:9], s46, v64
	v_readlane_b32 s57, v254, 6
	s_nop 0
	v_cndmask_b32_e64 v64, 0, v64, s[8:9]
	v_add_u32_e32 v66, 0xffff8000, v64
	v_ashrrev_i32_e32 v65, 31, v64
	v_cmp_gt_i32_e64 s[6:7], s39, v64
	s_nop 1
	v_cndmask_b32_e64 v65, 0, v65, s[6:7]
	v_cndmask_b32_e64 v64, v66, v64, s[6:7]
	v_cndmask_b32_e64 v67, v68, v69, s[6:7]
	v_cndmask_b32_e64 v66, v70, v71, s[6:7]
	v_lshlrev_b64 v[130:131], 12, v[64:65]
	v_lshl_add_u64 v[64:65], v[66:67], 0, v[130:131]
	v_lshl_add_u64 v[64:65], v[64:65], 0, v[214:215]
	global_load_dwordx4 v[92:95], v[64:65], off offset:16 nt
	global_load_dwordx4 v[88:91], v[64:65], off nt
	global_load_dwordx4 v[84:87], v[64:65], off offset:144 nt
	global_load_dwordx4 v[80:83], v[64:65], off offset:128 nt
	v_add_u32_e32 v64, 0xb0, v230
	v_cmp_gt_i32_e64 s[2:3], s46, v64
	s_nop 1
	v_cndmask_b32_e64 v64, 0, v64, s[2:3]
	v_add_u32_e32 v66, 0xffff8000, v64
	v_ashrrev_i32_e32 v65, 31, v64
	v_cmp_gt_i32_e32 vcc, s39, v64
	s_nop 1
	v_cndmask_b32_e32 v65, 0, v65, vcc
	v_cndmask_b32_e32 v64, v66, v64, vcc
	v_cndmask_b32_e32 v67, v68, v69, vcc
	v_cndmask_b32_e32 v66, v70, v71, vcc
	v_lshlrev_b64 v[128:129], 12, v[64:65]
	v_lshl_add_u64 v[64:65], v[66:67], 0, v[128:129]
	v_lshl_add_u64 v[64:65], v[64:65], 0, v[214:215]
	global_load_dwordx4 v[76:79], v[64:65], off offset:16 nt
	global_load_dwordx4 v[72:75], v[64:65], off nt
	global_load_dwordx4 v[68:71], v[64:65], off offset:144 nt
	s_nop 0
	global_load_dwordx4 v[64:67], v[64:65], off offset:128 nt
	s_and_saveexec_b64 s[28:29], s[16:17]
	s_cbranch_execnz .LBB0_1844
	s_or_b64 exec, exec, s[28:29]
	s_and_saveexec_b64 s[14:15], s[12:13]
	s_cbranch_execnz .LBB0_1845

;     __device__ __forceinline__ void operator()(const Acc& acc, const Unit& u, int wr, int wc, int fr, int fq) const {
;     ...
;             for (int m = 0; m < 4; ++m) {
;                 const int row = u.pm * 256 + ai * 128 + wr * 64 + m * 16 + fr;
;                 const bool ok = row < MREAL; const int rr = ok ? row : 0;
;                 float* dst = ((MODE == 2) ? y_row(P, rr) : x1_row(P, rr)) + colb;
;                 float part = 0.f;
; #pragma unroll
;                 for (int bj = 0; bj < 2; ++bj) {
;                     const f32x4 o0 = R[m][bj][0] + acc[ai][bj][m][0] * sc, o1 = R[m][bj][1] + acc[ai][bj][m][1] * sc;
;                     if (ok) {
;                         *(f32x4*)(dst + bj * 32) = o0; *(f32x4*)(dst + bj * 32 + 4) = o1;
.LBB0_1841:
	v_readlane_b32 s52, v254, 1
	v_cndmask_b32_e64 v200, v229, 0, s[14:15]
	v_readlane_b32 s58, v254, 7
	v_readlane_b32 s59, v254, 8
	s_waitcnt vmcnt(0)
	v_pk_fma_f32 v[122:123], v[122:123], 0.5, v[186:187] op_sel_hi:[1,0,1]
	v_pk_fma_f32 v[120:121], v[120:121], 0.5, v[184:185] op_sel_hi:[1,0,1]
	v_lshl_add_u64 v[232:233], s[58:59], 0, v[200:201]
	v_lshl_add_u64 v[222:223], v[232:233], 0, v[222:223]
	v_lshl_add_u64 v[222:223], v[212:213], 2, v[222:223]
	v_pk_fma_f32 v[114:115], v[114:115], 0.5, v[178:179] op_sel_hi:[1,0,1]
	v_pk_fma_f32 v[112:113], v[112:113], 0.5, v[176:177] op_sel_hi:[1,0,1]
	v_readlane_b32 s53, v254, 2
	v_readlane_b32 s54, v254, 3
	v_readlane_b32 s55, v254, 4
	v_readlane_b32 s56, v254, 5
	v_readlane_b32 s57, v254, 6
	v_pk_fma_f32 v[126:127], v[126:127], 0.5, v[190:191] op_sel_hi:[1,0,1]
	v_pk_fma_f32 v[124:125], v[124:125], 0.5, v[188:189] op_sel_hi:[1,0,1]
	global_store_dwordx4 v[222:223], v[120:123], off nt
	global_store_dwordx4 v[222:223], v[124:127], off offset:16 nt
	v_pk_fma_f32 v[118:119], v[118:119], 0.5, v[182:183] op_sel_hi:[1,0,1]
	v_pk_fma_f32 v[116:117], v[116:117], 0.5, v[180:181] op_sel_hi:[1,0,1]
	global_store_dwordx4 v[222:223], v[112:115], off offset:128 nt
	global_store_dwordx4 v[222:223], v[116:119], off offset:144 nt
	s_or_b64 exec, exec, s[28:29]
	s_and_saveexec_b64 s[14:15], s[12:13]
	s_cbranch_execz .LBB0_1833
.LBB0_1842:
	v_readlane_b32 s52, v254, 1
	v_cndmask_b32_e64 v200, v229, 0, s[10:11]
	v_readlane_b32 s58, v254, 7
	v_readlane_b32 s59, v254, 8
	s_waitcnt vmcnt(0)
	v_pk_fma_f32 v[106:107], v[106:107], 0.5, v[170:171] op_sel_hi:[1,0,1]
	v_pk_fma_f32 v[104:105], v[104:105], 0.5, v[168:169] op_sel_hi:[1,0,1]
	v_lshl_add_u64 v[112:113], s[58:59], 0, v[200:201]
	v_lshl_add_u64 v[112:113], v[112:113], 0, v[220:221]
	v_lshl_add_u64 v[112:113], v[212:213], 2, v[112:113]
	v_pk_fma_f32 v[98:99], v[98:99], 0.5, v[162:163] op_sel_hi:[1,0,1]
	v_pk_fma_f32 v[96:97], v[96:97], 0.5, v[160:161] op_sel_hi:[1,0,1]
	v_readlane_b32 s53, v254, 2
	v_readlane_b32 s54, v254, 3
	v_readlane_b32 s55, v254, 4
	v_readlane_b32 s56, v254, 5
	v_readlane_b32 s57, v254, 6
	v_pk_fma_f32 v[110:111], v[110:111], 0.5, v[174:175] op_sel_hi:[1,0,1]
	v_pk_fma_f32 v[108:109], v[108:109], 0.5, v[172:173] op_sel_hi:[1,0,1]
	global_store_dwordx4 v[112:113], v[104:107], off nt
	global_store_dwordx4 v[112:113], v[108:111], off offset:16 nt
	v_pk_fma_f32 v[102:103], v[102:103], 0.5, v[166:167] op_sel_hi:[1,0,1]
	v_pk_fma_f32 v[100:101], v[100:101], 0.5, v[164:165] op_sel_hi:[1,0,1]
	global_store_dwordx4 v[112:113], v[96:99], off offset:128 nt
	global_store_dwordx4 v[112:113], v[100:103], off offset:144 nt
	s_or_b64 exec, exec, s[14:15]
	s_and_saveexec_b64 s[10:11], s[8:9]
	s_cbranch_execz .LBB0_1834
.LBB0_1843:
	v_readlane_b32 s52, v254, 1
	v_cndmask_b32_e64 v200, v229, 0, s[6:7]
	v_readlane_b32 s58, v254, 7
	v_readlane_b32 s59, v254, 8
	s_waitcnt vmcnt(0)
	v_pk_fma_f32 v[90:91], v[90:91], 0.5, v[154:155] op_sel_hi:[1,0,1]
	v_pk_fma_f32 v[88:89], v[88:89], 0.5, v[152:153] op_sel_hi:[1,0,1]
	v_lshl_add_u64 v[96:97], s[58:59], 0, v[200:201]
	v_lshl_add_u64 v[96:97], v[96:97], 0, v[218:219]
	v_lshl_add_u64 v[96:97], v[212:213], 2, v[96:97]
	v_pk_fma_f32 v[82:83], v[82:83], 0.5, v[146:147] op_sel_hi:[1,0,1]
	v_pk_fma_f32 v[80:81], v[80:81], 0.5, v[144:145] op_sel_hi:[1,0,1]
	v_readlane_b32 s53, v254, 2
	v_readlane_b32 s54, v254, 3
	v_readlane_b32 s55, v254, 4
	v_readlane_b32 s56, v254, 5
	v_readlane_b32 s57, v254, 6
	v_pk_fma_f32 v[94:95], v[94:95], 0.5, v[158:159] op_sel_hi:[1,0,1]
	v_pk_fma_f32 v[92:93], v[92:93], 0.5, v[156:157] op_sel_hi:[1,0,1]
	global_store_dwordx4 v[96:97], v[88:91], off nt
	global_store_dwordx4 v[96:97], v[92:95], off offset:16 nt
	v_pk_fma_f32 v[86:87], v[86:87], 0.5, v[150:151] op_sel_hi:[1,0,1]
	v_pk_fma_f32 v[84:85], v[84:85], 0.5, v[148:149] op_sel_hi:[1,0,1]
	global_store_dwordx4 v[96:97], v[80:83], off offset:128 nt
	global_store_dwordx4 v[96:97], v[84:87], off offset:144 nt
	s_or_b64 exec, exec, s[10:11]
	s_and_saveexec_b64 s[6:7], s[2:3]
	s_cbranch_execnz .LBB0_1835
	s_branch .LBB0_1836
;     __device__ __forceinline__ void operator()(const Acc& acc, const Unit& u, int wr, int wc, int fr, int fq) const {
;     ...
;             for (int m = 0; m < 4; ++m) {
;                 const int row = u.pm * 256 + ai * 128 + wr * 64 + m * 16 + fr;
;                 const bool ok = row < MREAL; const int rr = ok ? row : 0;
;                 float* dst = ((MODE == 2) ? y_row(P, rr) : x1_row(P, rr)) + colb;
;                 float part = 0.f;
; #pragma unroll
;                 for (int bj = 0; bj < 2; ++bj) {
;                     const f32x4 o0 = R[m][bj][0] + acc[ai][bj][m][0] * sc, o1 = R[m][bj][1] + acc[ai][bj][m][1] * sc;
;                     if (ok) {
;                         *(f32x4*)(dst + bj * 32) = o0; *(f32x4*)(dst + bj * 32 + 4) = o1;
.LBB0_1844:
	v_readlane_b32 s52, v254, 1
	v_cndmask_b32_e64 v200, v229, 0, s[14:15]
	v_readlane_b32 s58, v254, 7
	v_readlane_b32 s59, v254, 8
	s_waitcnt vmcnt(14)
	v_pk_fma_f32 v[58:59], v[58:59], 0.5, v[122:123] op_sel_hi:[1,0,1]
	v_pk_fma_f32 v[56:57], v[56:57], 0.5, v[120:121] op_sel_hi:[1,0,1]
	v_lshl_add_u64 v[136:137], s[58:59], 0, v[200:201]
	v_lshl_add_u64 v[134:135], v[136:137], 0, v[134:135]
	v_lshl_add_u64 v[134:135], v[212:213], 2, v[134:135]
	s_waitcnt vmcnt(12)
	v_pk_fma_f32 v[50:51], v[50:51], 0.5, v[114:115] op_sel_hi:[1,0,1]
	v_pk_fma_f32 v[48:49], v[48:49], 0.5, v[112:113] op_sel_hi:[1,0,1]
	v_readlane_b32 s53, v254, 2
	v_readlane_b32 s54, v254, 3
	v_readlane_b32 s55, v254, 4
	v_readlane_b32 s56, v254, 5
	v_readlane_b32 s57, v254, 6
	v_pk_fma_f32 v[62:63], v[62:63], 0.5, v[126:127] op_sel_hi:[1,0,1]
	v_pk_fma_f32 v[60:61], v[60:61], 0.5, v[124:125] op_sel_hi:[1,0,1]
	global_store_dwordx4 v[134:135], v[56:59], off nt
	global_store_dwordx4 v[134:135], v[60:63], off offset:16 nt
	v_pk_fma_f32 v[54:55], v[54:55], 0.5, v[118:119] op_sel_hi:[1,0,1]
	v_pk_fma_f32 v[52:53], v[52:53], 0.5, v[116:117] op_sel_hi:[1,0,1]
	global_store_dwordx4 v[134:135], v[48:51], off offset:128 nt
	global_store_dwordx4 v[134:135], v[52:55], off offset:144 nt
	s_or_b64 exec, exec, s[28:29]
	s_and_saveexec_b64 s[14:15], s[12:13]
	s_cbranch_execz .LBB0_1838
.LBB0_1845:
	v_readlane_b32 s52, v254, 1
	v_cndmask_b32_e64 v200, v229, 0, s[10:11]
	v_readlane_b32 s58, v254, 7
	v_readlane_b32 s59, v254, 8
	s_waitcnt vmcnt(10)
	v_pk_fma_f32 v[42:43], v[42:43], 0.5, v[106:107] op_sel_hi:[1,0,1]
	v_pk_fma_f32 v[40:41], v[40:41], 0.5, v[104:105] op_sel_hi:[1,0,1]
	v_lshl_add_u64 v[48:49], s[58:59], 0, v[200:201]
	v_lshl_add_u64 v[48:49], v[48:49], 0, v[132:133]
	v_lshl_add_u64 v[48:49], v[212:213], 2, v[48:49]
	s_waitcnt vmcnt(8)
	v_pk_fma_f32 v[34:35], v[34:35], 0.5, v[98:99] op_sel_hi:[1,0,1]
	v_pk_fma_f32 v[32:33], v[32:33], 0.5, v[96:97] op_sel_hi:[1,0,1]
	v_readlane_b32 s53, v254, 2
	v_readlane_b32 s54, v254, 3
	v_readlane_b32 s55, v254, 4
	v_readlane_b32 s56, v254, 5
	v_readlane_b32 s57, v254, 6
	v_pk_fma_f32 v[46:47], v[46:47], 0.5, v[110:111] op_sel_hi:[1,0,1]
	v_pk_fma_f32 v[44:45], v[44:45], 0.5, v[108:109] op_sel_hi:[1,0,1]
	global_store_dwordx4 v[48:49], v[40:43], off nt
	global_store_dwordx4 v[48:49], v[44:47], off offset:16 nt
	v_pk_fma_f32 v[38:39], v[38:39], 0.5, v[102:103] op_sel_hi:[1,0,1]
	v_pk_fma_f32 v[36:37], v[36:37], 0.5, v[100:101] op_sel_hi:[1,0,1]
	global_store_dwordx4 v[48:49], v[32:35], off offset:128 nt
	global_store_dwordx4 v[48:49], v[36:39], off offset:144 nt
	s_or_b64 exec, exec, s[14:15]
	s_and_saveexec_b64 s[10:11], s[8:9]
	s_cbranch_execz .LBB0_1839
.LBB0_1846:
	v_readlane_b32 s52, v254, 1
	v_cndmask_b32_e64 v200, v229, 0, s[6:7]
	v_readlane_b32 s58, v254, 7
	v_readlane_b32 s59, v254, 8
	s_waitcnt vmcnt(6)
	v_pk_fma_f32 v[26:27], v[26:27], 0.5, v[90:91] op_sel_hi:[1,0,1]
	v_pk_fma_f32 v[24:25], v[24:25], 0.5, v[88:89] op_sel_hi:[1,0,1]
	v_lshl_add_u64 v[32:33], s[58:59], 0, v[200:201]
	v_lshl_add_u64 v[32:33], v[32:33], 0, v[130:131]
	v_lshl_add_u64 v[32:33], v[212:213], 2, v[32:33]
	s_waitcnt vmcnt(4)
	v_pk_fma_f32 v[18:19], v[18:19], 0.5, v[82:83] op_sel_hi:[1,0,1]
	v_pk_fma_f32 v[16:17], v[16:17], 0.5, v[80:81] op_sel_hi:[1,0,1]
	v_readlane_b32 s53, v254, 2
	v_readlane_b32 s54, v254, 3
	v_readlane_b32 s55, v254, 4
	v_readlane_b32 s56, v254, 5
	v_readlane_b32 s57, v254, 6
	v_pk_fma_f32 v[30:31], v[30:31], 0.5, v[94:95] op_sel_hi:[1,0,1]
	v_pk_fma_f32 v[28:29], v[28:29], 0.5, v[92:93] op_sel_hi:[1,0,1]
	global_store_dwordx4 v[32:33], v[24:27], off nt
	global_store_dwordx4 v[32:33], v[28:31], off offset:16 nt
	v_pk_fma_f32 v[22:23], v[22:23], 0.5, v[86:87] op_sel_hi:[1,0,1]
	v_pk_fma_f32 v[20:21], v[20:21], 0.5, v[84:85] op_sel_hi:[1,0,1]
	global_store_dwordx4 v[32:33], v[16:19], off offset:128 nt
	global_store_dwordx4 v[32:33], v[20:23], off offset:144 nt
	s_or_b64 exec, exec, s[10:11]
	s_and_saveexec_b64 s[6:7], s[2:3]
	s_cbranch_execz .LBB0_1840
.LBB0_1847:
	v_readlane_b32 s8, v254, 1
	v_cndmask_b32_e64 v200, v229, 0, vcc
	v_readlane_b32 s14, v254, 7
	v_readlane_b32 s15, v254, 8
	s_waitcnt vmcnt(2)
	v_pk_fma_f32 v[10:11], v[10:11], 0.5, v[74:75] op_sel_hi:[1,0,1]
	v_pk_fma_f32 v[8:9], v[8:9], 0.5, v[72:73] op_sel_hi:[1,0,1]
	v_lshl_add_u64 v[16:17], s[14:15], 0, v[200:201]
	v_lshl_add_u64 v[16:17], v[16:17], 0, v[128:129]
	v_lshl_add_u64 v[16:17], v[212:213], 2, v[16:17]
	s_waitcnt vmcnt(0)
	v_pk_fma_f32 v[6:7], v[6:7], 0.5, v[66:67] op_sel_hi:[1,0,1]
	v_pk_fma_f32 v[4:5], v[4:5], 0.5, v[64:65] op_sel_hi:[1,0,1]
	v_readlane_b32 s9, v254, 2
	v_readlane_b32 s10, v254, 3
	v_readlane_b32 s11, v254, 4
	v_readlane_b32 s12, v254, 5
	v_readlane_b32 s13, v254, 6
	v_pk_fma_f32 v[14:15], v[14:15], 0.5, v[78:79] op_sel_hi:[1,0,1]
	v_pk_fma_f32 v[12:13], v[12:13], 0.5, v[76:77] op_sel_hi:[1,0,1]
	global_store_dwordx4 v[16:17], v[8:11], off nt
	global_store_dwordx4 v[16:17], v[12:15], off offset:16 nt
	v_pk_fma_f32 v[2:3], v[2:3], 0.5, v[70:71] op_sel_hi:[1,0,1]
	v_pk_fma_f32 v[0:1], v[0:1], 0.5, v[68:69] op_sel_hi:[1,0,1]
	global_store_dwordx4 v[16:17], v[4:7], off offset:128 nt
	global_store_dwordx4 v[16:17], v[0:3], off offset:144 nt
	s_or_b64 exec, exec, s[6:7]
	s_and_b64 vcc, exec, s[0:1]
	s_mov_b64 s[0:1], -1
	s_cbranch_vccnz .LBB0_1816
